# adds the transposed value image (one ds_read_b128 per four steps for the value scalars in the recurrence waves) to the placement-compensated combination
# speedup vs baseline: 1.0053x; 1.0053x over previous
.LBB0_944:
	s_cmp_lt_u32 s35, 0x40001
	s_mov_b64 s[64:65], 0
	s_cselect_b64 s[66:67], -1, 0
	s_mov_b64 s[74:75], -1
	s_and_b64 vcc, exec, s[66:67]
	s_cbranch_vccz .LBB0_938
	s_branch .LBB0_943
	s_nop 0
	s_nop 0
	s_nop 0
	s_nop 0
	s_nop 0
	s_nop 0
	s_nop 0
	s_nop 0
	s_nop 0
	s_nop 0
	s_nop 0
	s_nop 0
	s_nop 0
	s_nop 0

.LBB0_1044:
	v_readlane_b32 s0, v255, 40
	v_readlane_b32 s1, v255, 41
	s_andn2_b64 vcc, exec, s[0:1]
	s_cbranch_vccnz .LBB0_1103
	s_and_b32 s6, s2, 3
	v_readlane_b32 s7, v255, 0
	s_mov_b64 s[0:1], -1
	s_cmpk_lt_u32 s7, 0x100
	v_lshlrev_b32_e32 v22, 3, v169
	s_cbranch_scc0 .LBB0_1049
	v_readlane_b32 s1, v255, 5
	s_lshl_b32 s0, s6, 4
	s_lshl_b32 s1, s1, 2
	s_or_b32 s0, s1, s0
	v_or_b32_e32 v6, s0, v166
	s_setprio 3
	v_or_b32_e32 v2, s1, v166
	s_movk_i32 s0, 0x90
	v_mul_lo_u32 v2, v2, s0
	v_readlane_b32 s7, v255, 5
	s_add_i32 s7, s7, 1
	s_and_b32 s7, s7, 2
	s_lshl_b32 s7, s7, 3
	v_xor_b32_e32 v118, s7, v22
	v_add3_u32 v7, 0, v2, v118
	v_mov_b32_e32 v2, 0
	s_mov_b32 s0, 0
	v_mov_b32_e32 v3, v2
	v_mov_b32_e32 v4, v2
	v_mov_b32_e32 v5, v2
	v_lshlrev_b32_e32 v9, 4, v169
	v_lshrrev_b32_e32 v134, 2, v6
	v_and_b32_e32 v135, 3, v6
	v_lshl_add_u32 v134, v135, 2, v134
	v_and_b32_e32 v134, 15, v134
	v_lshl_add_u32 v134, v135, 4, v134
	v_lshlrev_b32_e32 v134, 4, v134
	v_add_u32_e32 v135, 0x1e000, v134
	v_add_u32_e32 v134, 0x1d000, v134
	v_mov_b32_e32 v11, v7
	v_add_u32_e32 v8, 0xb000, v7
	v_add_u32_e32 v114, 0x5000, v9
	v_add_u32_e32 v116, 0x9000, v7
	v_add_u32_e32 v117, 0x9000, v8
	s_barrier
.LBB0_1047:
	ds_read_b128 v[44:47], v9 offset:256
	ds_read_b128 v[40:43], v9
	ds_read_b128 v[52:55], v9 offset:768
	ds_read_b128 v[120:123], v134
	ds_read_b128 v[48:51], v9 offset:512
	ds_read_b128 v[80:83], v9 offset:1536
	ds_read_b128 v[76:79], v9 offset:1280
	ds_read_b128 v[88:91], v9 offset:2048
	ds_read_b128 v[84:87], v9 offset:1792
	s_waitcnt lgkmcnt(8)
	v_pk_mul_f32 v[58:59], v[44:45], v[2:3]
	s_waitcnt lgkmcnt(7)
	v_pk_mul_f32 v[60:61], v[40:41], v[2:3]
	v_pk_fma_f32 v[58:59], v[46:47], v[4:5], v[58:59]
	v_pk_mul_f32 v[62:63], v[42:43], v[4:5]
	v_add_f32_e32 v64, v58, v59
	s_waitcnt lgkmcnt(5)
	v_pk_fma_f32 v[60:61], v[52:53], v[120:121], v[60:61] op_sel_hi:[1,0,1]
	v_pk_fma_f32 v[62:63], v[54:55], v[120:121], v[62:63] op_sel_hi:[1,0,1]
	v_add_f32_dpp v65, v64, v64 quad_perm:[1,0,3,2] row_mask:0xf bank_mask:0xf bound_ctrl:1
	ds_read_b128 v[100:103], v9 offset:2816
	ds_read_b128 v[96:99], v9 offset:2560
	v_add_f32_dpp v64, v65, v65 quad_perm:[2,3,0,1] row_mask:0xf bank_mask:0xf bound_ctrl:1
	ds_read_b128 v[108:111], v9 offset:3328
	ds_read_b128 v[104:107], v9 offset:3072
	v_add_f32_dpp v65, v64, v64 row_half_mirror row_mask:0xf bank_mask:0xf bound_ctrl:1
	s_nop 0
	s_nop 0
	v_add_f32_dpp v66, v65, v65 row_mirror row_mask:0xf bank_mask:0xf bound_ctrl:1
	s_waitcnt lgkmcnt(8)
	v_pk_fma_f32 v[2:3], v[48:49], v[66:67], v[60:61] op_sel_hi:[1,0,1]
	v_pk_fma_f32 v[4:5], v[50:51], v[66:67], v[62:63] op_sel_hi:[1,0,1]
	s_waitcnt lgkmcnt(4)
	v_pk_mul_f32 v[58:59], v[80:81], v[2:3]
	v_pk_mul_f32 v[60:61], v[76:77], v[2:3]
	v_pk_fma_f32 v[58:59], v[82:83], v[4:5], v[58:59]
	v_pk_mul_f32 v[62:63], v[78:79], v[4:5]
	v_add_f32_e32 v64, v58, v59
	v_pk_fma_f32 v[60:61], v[88:89], v[120:121], v[60:61] op_sel:[0,1,0]
	v_pk_fma_f32 v[62:63], v[90:91], v[120:121], v[62:63] op_sel:[0,1,0]
	v_add_f32_dpp v65, v64, v64 quad_perm:[1,0,3,2] row_mask:0xf bank_mask:0xf bound_ctrl:1
	v_cvt_pk_bf16_f32 v68, v2, v3
	v_cvt_pk_bf16_f32 v69, v4, v5
	v_add_f32_dpp v64, v65, v65 quad_perm:[2,3,0,1] row_mask:0xf bank_mask:0xf bound_ctrl:1
	ds_write_b64 v11, v[68:69] offset:45056
	ds_read_b128 v[44:47], v9 offset:4096
	v_add_f32_dpp v65, v64, v64 row_half_mirror row_mask:0xf bank_mask:0xf bound_ctrl:1
	ds_read_b128 v[40:43], v9 offset:3840
	ds_read_b128 v[52:55], v9 offset:4608
	v_add_f32_dpp v66, v65, v65 row_mirror row_mask:0xf bank_mask:0xf bound_ctrl:1
	v_pk_fma_f32 v[2:3], v[84:85], v[66:67], v[60:61] op_sel_hi:[1,0,1]
	v_pk_fma_f32 v[4:5], v[86:87], v[66:67], v[62:63] op_sel_hi:[1,0,1]
	ds_read_b128 v[48:51], v9 offset:4352
	s_waitcnt lgkmcnt(5)
	v_pk_mul_f32 v[58:59], v[100:101], v[2:3]
	v_pk_mul_f32 v[60:61], v[96:97], v[2:3]
	v_pk_fma_f32 v[58:59], v[102:103], v[4:5], v[58:59]
	v_pk_mul_f32 v[62:63], v[98:99], v[4:5]
	v_add_f32_e32 v64, v58, v59
	v_pk_fma_f32 v[60:61], v[108:109], v[122:123], v[60:61] op_sel_hi:[1,0,1]
	v_pk_fma_f32 v[62:63], v[110:111], v[122:123], v[62:63] op_sel_hi:[1,0,1]
	v_add_f32_dpp v65, v64, v64 quad_perm:[1,0,3,2] row_mask:0xf bank_mask:0xf bound_ctrl:1
	v_cvt_pk_bf16_f32 v70, v2, v3
	v_cvt_pk_bf16_f32 v71, v4, v5
	v_add_f32_dpp v64, v65, v65 quad_perm:[2,3,0,1] row_mask:0xf bank_mask:0xf bound_ctrl:1
	ds_write_b64 v11, v[70:71] offset:47360
	ds_read_b128 v[80:83], v9 offset:5376
	v_add_f32_dpp v65, v64, v64 row_half_mirror row_mask:0xf bank_mask:0xf bound_ctrl:1
	ds_read_b128 v[76:79], v9 offset:5120
	ds_read_b128 v[88:91], v9 offset:5888
	v_add_f32_dpp v66, v65, v65 row_mirror row_mask:0xf bank_mask:0xf bound_ctrl:1
	v_pk_fma_f32 v[2:3], v[104:105], v[66:67], v[60:61] op_sel_hi:[1,0,1]
	v_pk_fma_f32 v[4:5], v[106:107], v[66:67], v[62:63] op_sel_hi:[1,0,1]
	ds_read_b128 v[124:127], v134 offset:1024
	ds_read_b128 v[84:87], v9 offset:5632
	s_waitcnt lgkmcnt(6)
	v_pk_mul_f32 v[58:59], v[44:45], v[2:3]
	v_pk_mul_f32 v[60:61], v[40:41], v[2:3]
	v_pk_fma_f32 v[58:59], v[46:47], v[4:5], v[58:59]
	v_pk_mul_f32 v[62:63], v[42:43], v[4:5]
	v_add_f32_e32 v64, v58, v59
	v_pk_fma_f32 v[60:61], v[52:53], v[122:123], v[60:61] op_sel:[0,1,0]
	v_pk_fma_f32 v[62:63], v[54:55], v[122:123], v[62:63] op_sel:[0,1,0]
	v_add_f32_dpp v65, v64, v64 quad_perm:[1,0,3,2] row_mask:0xf bank_mask:0xf bound_ctrl:1
	v_cvt_pk_bf16_f32 v68, v2, v3
	v_cvt_pk_bf16_f32 v69, v4, v5
	v_add_f32_dpp v64, v65, v65 quad_perm:[2,3,0,1] row_mask:0xf bank_mask:0xf bound_ctrl:1
	ds_write_b64 v11, v[68:69] offset:49664
	ds_read_b128 v[100:103], v9 offset:6656
	v_add_f32_dpp v65, v64, v64 row_half_mirror row_mask:0xf bank_mask:0xf bound_ctrl:1
	ds_read_b128 v[96:99], v9 offset:6400
	ds_read_b128 v[108:111], v9 offset:7168
	v_add_f32_dpp v66, v65, v65 row_mirror row_mask:0xf bank_mask:0xf bound_ctrl:1
	v_pk_fma_f32 v[2:3], v[48:49], v[66:67], v[60:61] op_sel_hi:[1,0,1]
	v_pk_fma_f32 v[4:5], v[50:51], v[66:67], v[62:63] op_sel_hi:[1,0,1]
	ds_read_b128 v[104:107], v9 offset:6912
	s_waitcnt lgkmcnt(5)
	v_pk_mul_f32 v[58:59], v[80:81], v[2:3]
	v_pk_mul_f32 v[60:61], v[76:77], v[2:3]
	v_pk_fma_f32 v[58:59], v[82:83], v[4:5], v[58:59]
	v_pk_mul_f32 v[62:63], v[78:79], v[4:5]
	v_add_f32_e32 v64, v58, v59
	v_pk_fma_f32 v[60:61], v[88:89], v[124:125], v[60:61] op_sel_hi:[1,0,1]
	v_pk_fma_f32 v[62:63], v[90:91], v[124:125], v[62:63] op_sel_hi:[1,0,1]
	v_add_f32_dpp v65, v64, v64 quad_perm:[1,0,3,2] row_mask:0xf bank_mask:0xf bound_ctrl:1
	v_cvt_pk_bf16_f32 v70, v2, v3
	v_cvt_pk_bf16_f32 v71, v4, v5
	v_add_f32_dpp v64, v65, v65 quad_perm:[2,3,0,1] row_mask:0xf bank_mask:0xf bound_ctrl:1
	ds_write_b64 v11, v[70:71] offset:51968
	ds_read_b128 v[44:47], v9 offset:7936
	v_add_f32_dpp v65, v64, v64 row_half_mirror row_mask:0xf bank_mask:0xf bound_ctrl:1
	ds_read_b128 v[40:43], v9 offset:7680
	ds_read_b128 v[52:55], v9 offset:8448
	v_add_f32_dpp v66, v65, v65 row_mirror row_mask:0xf bank_mask:0xf bound_ctrl:1
	v_pk_fma_f32 v[2:3], v[84:85], v[66:67], v[60:61] op_sel_hi:[1,0,1]
	v_pk_fma_f32 v[4:5], v[86:87], v[66:67], v[62:63] op_sel_hi:[1,0,1]
	ds_read_b128 v[48:51], v9 offset:8192
	s_waitcnt lgkmcnt(5)
	v_pk_mul_f32 v[58:59], v[100:101], v[2:3]
	v_pk_mul_f32 v[60:61], v[96:97], v[2:3]
	v_pk_fma_f32 v[58:59], v[102:103], v[4:5], v[58:59]
	v_pk_mul_f32 v[62:63], v[98:99], v[4:5]
	v_add_f32_e32 v64, v58, v59
	v_pk_fma_f32 v[60:61], v[108:109], v[124:125], v[60:61] op_sel:[0,1,0]
	v_pk_fma_f32 v[62:63], v[110:111], v[124:125], v[62:63] op_sel:[0,1,0]
	v_add_f32_dpp v65, v64, v64 quad_perm:[1,0,3,2] row_mask:0xf bank_mask:0xf bound_ctrl:1
	v_cvt_pk_bf16_f32 v68, v2, v3
	v_cvt_pk_bf16_f32 v69, v4, v5
	v_add_f32_dpp v64, v65, v65 quad_perm:[2,3,0,1] row_mask:0xf bank_mask:0xf bound_ctrl:1
	ds_write_b64 v11, v[68:69] offset:54272
	ds_read_b128 v[80:83], v9 offset:9216
	v_add_f32_dpp v65, v64, v64 row_half_mirror row_mask:0xf bank_mask:0xf bound_ctrl:1
	ds_read_b128 v[76:79], v9 offset:8960
	ds_read_b128 v[88:91], v9 offset:9728
	v_add_f32_dpp v66, v65, v65 row_mirror row_mask:0xf bank_mask:0xf bound_ctrl:1
	v_pk_fma_f32 v[2:3], v[104:105], v[66:67], v[60:61] op_sel_hi:[1,0,1]
	v_pk_fma_f32 v[4:5], v[106:107], v[66:67], v[62:63] op_sel_hi:[1,0,1]
	ds_read_b128 v[84:87], v9 offset:9472
	s_waitcnt lgkmcnt(5)
	v_pk_mul_f32 v[58:59], v[44:45], v[2:3]
	v_pk_mul_f32 v[60:61], v[40:41], v[2:3]
	v_pk_fma_f32 v[58:59], v[46:47], v[4:5], v[58:59]
	v_pk_mul_f32 v[62:63], v[42:43], v[4:5]
	v_add_f32_e32 v64, v58, v59
	v_pk_fma_f32 v[60:61], v[52:53], v[126:127], v[60:61] op_sel_hi:[1,0,1]
	v_pk_fma_f32 v[62:63], v[54:55], v[126:127], v[62:63] op_sel_hi:[1,0,1]
	v_add_f32_dpp v65, v64, v64 quad_perm:[1,0,3,2] row_mask:0xf bank_mask:0xf bound_ctrl:1
	v_cvt_pk_bf16_f32 v70, v2, v3
	v_cvt_pk_bf16_f32 v71, v4, v5
	v_add_f32_dpp v64, v65, v65 quad_perm:[2,3,0,1] row_mask:0xf bank_mask:0xf bound_ctrl:1
	ds_write_b64 v11, v[70:71] offset:56576
	ds_read_b128 v[100:103], v9 offset:10496
	v_add_f32_dpp v65, v64, v64 row_half_mirror row_mask:0xf bank_mask:0xf bound_ctrl:1
	ds_read_b128 v[96:99], v9 offset:10240
	ds_read_b128 v[108:111], v9 offset:11008
	v_add_f32_dpp v66, v65, v65 row_mirror row_mask:0xf bank_mask:0xf bound_ctrl:1
	v_pk_fma_f32 v[2:3], v[48:49], v[66:67], v[60:61] op_sel_hi:[1,0,1]
	v_pk_fma_f32 v[4:5], v[50:51], v[66:67], v[62:63] op_sel_hi:[1,0,1]
	ds_read_b128 v[128:131], v134 offset:2048
	ds_read_b128 v[104:107], v9 offset:10752
	s_waitcnt lgkmcnt(6)
	v_pk_mul_f32 v[58:59], v[80:81], v[2:3]
	v_pk_mul_f32 v[60:61], v[76:77], v[2:3]
	v_pk_fma_f32 v[58:59], v[82:83], v[4:5], v[58:59]
	v_pk_mul_f32 v[62:63], v[78:79], v[4:5]
	v_add_f32_e32 v64, v58, v59
	v_pk_fma_f32 v[60:61], v[88:89], v[126:127], v[60:61] op_sel:[0,1,0]
	v_pk_fma_f32 v[62:63], v[90:91], v[126:127], v[62:63] op_sel:[0,1,0]
	v_add_f32_dpp v65, v64, v64 quad_perm:[1,0,3,2] row_mask:0xf bank_mask:0xf bound_ctrl:1
	v_cvt_pk_bf16_f32 v68, v2, v3
	v_cvt_pk_bf16_f32 v69, v4, v5
	v_add_f32_dpp v64, v65, v65 quad_perm:[2,3,0,1] row_mask:0xf bank_mask:0xf bound_ctrl:1
	ds_write_b64 v11, v[68:69] offset:58880
	ds_read_b128 v[44:47], v9 offset:11776
	v_add_f32_dpp v65, v64, v64 row_half_mirror row_mask:0xf bank_mask:0xf bound_ctrl:1
	ds_read_b128 v[40:43], v9 offset:11520
	ds_read_b128 v[52:55], v9 offset:12288
	v_add_f32_dpp v66, v65, v65 row_mirror row_mask:0xf bank_mask:0xf bound_ctrl:1
	v_pk_fma_f32 v[2:3], v[84:85], v[66:67], v[60:61] op_sel_hi:[1,0,1]
	v_pk_fma_f32 v[4:5], v[86:87], v[66:67], v[62:63] op_sel_hi:[1,0,1]
	ds_read_b128 v[48:51], v9 offset:12032
	s_waitcnt lgkmcnt(5)
	v_pk_mul_f32 v[58:59], v[100:101], v[2:3]
	v_pk_mul_f32 v[60:61], v[96:97], v[2:3]
	v_pk_fma_f32 v[58:59], v[102:103], v[4:5], v[58:59]
	v_pk_mul_f32 v[62:63], v[98:99], v[4:5]
	v_add_f32_e32 v64, v58, v59
	v_pk_fma_f32 v[60:61], v[108:109], v[128:129], v[60:61] op_sel_hi:[1,0,1]
	v_pk_fma_f32 v[62:63], v[110:111], v[128:129], v[62:63] op_sel_hi:[1,0,1]
	v_add_f32_dpp v65, v64, v64 quad_perm:[1,0,3,2] row_mask:0xf bank_mask:0xf bound_ctrl:1
	v_cvt_pk_bf16_f32 v70, v2, v3
	v_cvt_pk_bf16_f32 v71, v4, v5
	v_add_f32_dpp v64, v65, v65 quad_perm:[2,3,0,1] row_mask:0xf bank_mask:0xf bound_ctrl:1
	ds_write_b64 v11, v[70:71] offset:61184
	ds_read_b128 v[80:83], v9 offset:13056
	v_add_f32_dpp v65, v64, v64 row_half_mirror row_mask:0xf bank_mask:0xf bound_ctrl:1
	ds_read_b128 v[76:79], v9 offset:12800
	ds_read_b128 v[88:91], v9 offset:13568
	v_add_f32_dpp v66, v65, v65 row_mirror row_mask:0xf bank_mask:0xf bound_ctrl:1
	v_pk_fma_f32 v[2:3], v[104:105], v[66:67], v[60:61] op_sel_hi:[1,0,1]
	v_pk_fma_f32 v[4:5], v[106:107], v[66:67], v[62:63] op_sel_hi:[1,0,1]
	ds_read_b128 v[84:87], v9 offset:13312
	s_waitcnt lgkmcnt(5)
	v_pk_mul_f32 v[58:59], v[44:45], v[2:3]
	v_pk_mul_f32 v[60:61], v[40:41], v[2:3]
	v_pk_fma_f32 v[58:59], v[46:47], v[4:5], v[58:59]
	v_pk_mul_f32 v[62:63], v[42:43], v[4:5]
	v_add_f32_e32 v64, v58, v59
	v_pk_fma_f32 v[60:61], v[52:53], v[128:129], v[60:61] op_sel:[0,1,0]
	v_pk_fma_f32 v[62:63], v[54:55], v[128:129], v[62:63] op_sel:[0,1,0]
	v_add_f32_dpp v65, v64, v64 quad_perm:[1,0,3,2] row_mask:0xf bank_mask:0xf bound_ctrl:1
	v_cvt_pk_bf16_f32 v68, v2, v3
	v_cvt_pk_bf16_f32 v69, v4, v5
	v_add_f32_dpp v64, v65, v65 quad_perm:[2,3,0,1] row_mask:0xf bank_mask:0xf bound_ctrl:1
	ds_write_b64 v11, v[68:69] offset:63488
	ds_read_b128 v[100:103], v9 offset:14336
	v_add_f32_dpp v65, v64, v64 row_half_mirror row_mask:0xf bank_mask:0xf bound_ctrl:1
	ds_read_b128 v[96:99], v9 offset:14080
	ds_read_b128 v[108:111], v9 offset:14848
	v_add_f32_dpp v66, v65, v65 row_mirror row_mask:0xf bank_mask:0xf bound_ctrl:1
	v_pk_fma_f32 v[2:3], v[48:49], v[66:67], v[60:61] op_sel_hi:[1,0,1]
	v_pk_fma_f32 v[4:5], v[50:51], v[66:67], v[62:63] op_sel_hi:[1,0,1]
	ds_read_b128 v[104:107], v9 offset:14592
	s_waitcnt lgkmcnt(5)
	v_pk_mul_f32 v[58:59], v[80:81], v[2:3]
	v_pk_mul_f32 v[60:61], v[76:77], v[2:3]
	v_pk_fma_f32 v[58:59], v[82:83], v[4:5], v[58:59]
	v_pk_mul_f32 v[62:63], v[78:79], v[4:5]
	v_add_f32_e32 v64, v58, v59
	v_pk_fma_f32 v[60:61], v[88:89], v[130:131], v[60:61] op_sel_hi:[1,0,1]
	v_pk_fma_f32 v[62:63], v[90:91], v[130:131], v[62:63] op_sel_hi:[1,0,1]
	v_add_f32_dpp v65, v64, v64 quad_perm:[1,0,3,2] row_mask:0xf bank_mask:0xf bound_ctrl:1
	v_cvt_pk_bf16_f32 v70, v2, v3
	v_cvt_pk_bf16_f32 v71, v4, v5
	v_add_f32_dpp v64, v65, v65 quad_perm:[2,3,0,1] row_mask:0xf bank_mask:0xf bound_ctrl:1
	ds_write_b64 v8, v[70:71] offset:20736
	ds_read_b128 v[44:47], v9 offset:15616
	v_add_f32_dpp v65, v64, v64 row_half_mirror row_mask:0xf bank_mask:0xf bound_ctrl:1
	ds_read_b128 v[40:43], v9 offset:15360
	ds_read_b128 v[52:55], v9 offset:16128
	v_add_f32_dpp v66, v65, v65 row_mirror row_mask:0xf bank_mask:0xf bound_ctrl:1
	v_pk_fma_f32 v[2:3], v[84:85], v[66:67], v[60:61] op_sel_hi:[1,0,1]
	v_pk_fma_f32 v[4:5], v[86:87], v[66:67], v[62:63] op_sel_hi:[1,0,1]
	ds_read_b128 v[136:139], v134 offset:3072
	ds_read_b128 v[48:51], v9 offset:15872
	s_waitcnt lgkmcnt(6)
	v_pk_mul_f32 v[58:59], v[100:101], v[2:3]
	v_pk_mul_f32 v[60:61], v[96:97], v[2:3]
	v_pk_fma_f32 v[58:59], v[102:103], v[4:5], v[58:59]
	v_pk_mul_f32 v[62:63], v[98:99], v[4:5]
	v_add_f32_e32 v64, v58, v59
	v_pk_fma_f32 v[60:61], v[108:109], v[130:131], v[60:61] op_sel:[0,1,0]
	v_pk_fma_f32 v[62:63], v[110:111], v[130:131], v[62:63] op_sel:[0,1,0]
	v_add_f32_dpp v65, v64, v64 quad_perm:[1,0,3,2] row_mask:0xf bank_mask:0xf bound_ctrl:1
	v_cvt_pk_bf16_f32 v68, v2, v3
	v_cvt_pk_bf16_f32 v69, v4, v5
	v_add_f32_dpp v64, v65, v65 quad_perm:[2,3,0,1] row_mask:0xf bank_mask:0xf bound_ctrl:1
	ds_write_b64 v8, v[68:69] offset:23040
	ds_read_b128 v[80:83], v9 offset:16896
	v_add_f32_dpp v65, v64, v64 row_half_mirror row_mask:0xf bank_mask:0xf bound_ctrl:1
	ds_read_b128 v[76:79], v9 offset:16640
	ds_read_b128 v[88:91], v9 offset:17408
	v_add_f32_dpp v66, v65, v65 row_mirror row_mask:0xf bank_mask:0xf bound_ctrl:1
	v_pk_fma_f32 v[2:3], v[104:105], v[66:67], v[60:61] op_sel_hi:[1,0,1]
	v_pk_fma_f32 v[4:5], v[106:107], v[66:67], v[62:63] op_sel_hi:[1,0,1]
	ds_read_b128 v[84:87], v9 offset:17152
	s_waitcnt lgkmcnt(5)
	v_pk_mul_f32 v[58:59], v[44:45], v[2:3]
	v_pk_mul_f32 v[60:61], v[40:41], v[2:3]
	v_pk_fma_f32 v[58:59], v[46:47], v[4:5], v[58:59]
	v_pk_mul_f32 v[62:63], v[42:43], v[4:5]
	v_add_f32_e32 v64, v58, v59
	v_pk_fma_f32 v[60:61], v[52:53], v[136:137], v[60:61] op_sel_hi:[1,0,1]
	v_pk_fma_f32 v[62:63], v[54:55], v[136:137], v[62:63] op_sel_hi:[1,0,1]
	v_add_f32_dpp v65, v64, v64 quad_perm:[1,0,3,2] row_mask:0xf bank_mask:0xf bound_ctrl:1
	v_cvt_pk_bf16_f32 v70, v2, v3
	v_cvt_pk_bf16_f32 v71, v4, v5
	v_add_f32_dpp v64, v65, v65 quad_perm:[2,3,0,1] row_mask:0xf bank_mask:0xf bound_ctrl:1
	ds_write_b64 v8, v[70:71] offset:25344
	ds_read_b128 v[100:103], v9 offset:18176
	v_add_f32_dpp v65, v64, v64 row_half_mirror row_mask:0xf bank_mask:0xf bound_ctrl:1
	ds_read_b128 v[96:99], v9 offset:17920
	ds_read_b128 v[108:111], v9 offset:18688
	v_add_f32_dpp v66, v65, v65 row_mirror row_mask:0xf bank_mask:0xf bound_ctrl:1
	v_pk_fma_f32 v[2:3], v[48:49], v[66:67], v[60:61] op_sel_hi:[1,0,1]
	v_pk_fma_f32 v[4:5], v[50:51], v[66:67], v[62:63] op_sel_hi:[1,0,1]
	ds_read_b128 v[104:107], v9 offset:18432
	s_waitcnt lgkmcnt(5)
	v_pk_mul_f32 v[58:59], v[80:81], v[2:3]
	v_pk_mul_f32 v[60:61], v[76:77], v[2:3]
	v_pk_fma_f32 v[58:59], v[82:83], v[4:5], v[58:59]
	v_pk_mul_f32 v[62:63], v[78:79], v[4:5]
	v_add_f32_e32 v64, v58, v59
	v_pk_fma_f32 v[60:61], v[88:89], v[136:137], v[60:61] op_sel:[0,1,0]
	v_pk_fma_f32 v[62:63], v[90:91], v[136:137], v[62:63] op_sel:[0,1,0]
	v_add_f32_dpp v65, v64, v64 quad_perm:[1,0,3,2] row_mask:0xf bank_mask:0xf bound_ctrl:1
	v_cvt_pk_bf16_f32 v68, v2, v3
	v_cvt_pk_bf16_f32 v69, v4, v5
	v_add_f32_dpp v64, v65, v65 quad_perm:[2,3,0,1] row_mask:0xf bank_mask:0xf bound_ctrl:1
	ds_write_b64 v8, v[68:69] offset:27648
	ds_read_b128 v[44:47], v9 offset:19456
	v_add_f32_dpp v65, v64, v64 row_half_mirror row_mask:0xf bank_mask:0xf bound_ctrl:1
	ds_read_b128 v[40:43], v9 offset:19200
	ds_read_b128 v[52:55], v9 offset:19968
	v_add_f32_dpp v66, v65, v65 row_mirror row_mask:0xf bank_mask:0xf bound_ctrl:1
	v_pk_fma_f32 v[2:3], v[84:85], v[66:67], v[60:61] op_sel_hi:[1,0,1]
	v_pk_fma_f32 v[4:5], v[86:87], v[66:67], v[62:63] op_sel_hi:[1,0,1]
	ds_read_b128 v[48:51], v9 offset:19712
	s_waitcnt lgkmcnt(5)
	v_pk_mul_f32 v[58:59], v[100:101], v[2:3]
	v_pk_mul_f32 v[60:61], v[96:97], v[2:3]
	v_pk_fma_f32 v[58:59], v[102:103], v[4:5], v[58:59]
	v_pk_mul_f32 v[62:63], v[98:99], v[4:5]
	v_add_f32_e32 v64, v58, v59
	v_pk_fma_f32 v[60:61], v[108:109], v[138:139], v[60:61] op_sel_hi:[1,0,1]
	v_pk_fma_f32 v[62:63], v[110:111], v[138:139], v[62:63] op_sel_hi:[1,0,1]
	v_add_f32_dpp v65, v64, v64 quad_perm:[1,0,3,2] row_mask:0xf bank_mask:0xf bound_ctrl:1
	v_cvt_pk_bf16_f32 v70, v2, v3
	v_cvt_pk_bf16_f32 v71, v4, v5
	v_add_f32_dpp v64, v65, v65 quad_perm:[2,3,0,1] row_mask:0xf bank_mask:0xf bound_ctrl:1
	ds_write_b64 v8, v[70:71] offset:29952
	s_nop 0
	v_add_f32_dpp v65, v64, v64 row_half_mirror row_mask:0xf bank_mask:0xf bound_ctrl:1
	s_nop 0
	s_nop 0
	v_add_f32_dpp v66, v65, v65 row_mirror row_mask:0xf bank_mask:0xf bound_ctrl:1
	v_pk_fma_f32 v[2:3], v[104:105], v[66:67], v[60:61] op_sel_hi:[1,0,1]
	v_pk_fma_f32 v[4:5], v[106:107], v[66:67], v[62:63] op_sel_hi:[1,0,1]
	s_waitcnt lgkmcnt(1)
	v_pk_mul_f32 v[58:59], v[44:45], v[2:3]
	v_pk_mul_f32 v[60:61], v[40:41], v[2:3]
	v_pk_fma_f32 v[58:59], v[46:47], v[4:5], v[58:59]
	v_pk_mul_f32 v[62:63], v[42:43], v[4:5]
	v_add_f32_e32 v64, v58, v59
	v_pk_fma_f32 v[60:61], v[52:53], v[138:139], v[60:61] op_sel:[0,1,0]
	v_pk_fma_f32 v[62:63], v[54:55], v[138:139], v[62:63] op_sel:[0,1,0]
	v_add_f32_dpp v65, v64, v64 quad_perm:[1,0,3,2] row_mask:0xf bank_mask:0xf bound_ctrl:1
	v_cvt_pk_bf16_f32 v68, v2, v3
	v_cvt_pk_bf16_f32 v69, v4, v5
	v_add_f32_dpp v64, v65, v65 quad_perm:[2,3,0,1] row_mask:0xf bank_mask:0xf bound_ctrl:1
	ds_write_b64 v8, v[68:69] offset:32256
	s_nop 0
	v_add_f32_dpp v65, v64, v64 row_half_mirror row_mask:0xf bank_mask:0xf bound_ctrl:1
	s_nop 0
	s_nop 0
	v_add_f32_dpp v66, v65, v65 row_mirror row_mask:0xf bank_mask:0xf bound_ctrl:1
	v_pk_fma_f32 v[2:3], v[48:49], v[66:67], v[60:61] op_sel_hi:[1,0,1]
	v_pk_fma_f32 v[4:5], v[50:51], v[66:67], v[62:63] op_sel_hi:[1,0,1]
	v_cvt_pk_bf16_f32 v70, v2, v3
	v_cvt_pk_bf16_f32 v71, v4, v5
	ds_write_b64 v8, v[70:71] offset:34560
	s_add_i32 s0, s0, 1
	s_cmpk_eq_i32 s0, 0x201
	s_waitcnt lgkmcnt(0)
	s_barrier
	s_cbranch_scc1 .Lscan_done
	ds_read_b128 v[44:47], v114 offset:256
	ds_read_b128 v[40:43], v114
	ds_read_b128 v[52:55], v114 offset:768
	ds_read_b128 v[120:123], v135
	ds_read_b128 v[48:51], v114 offset:512
	ds_read_b128 v[80:83], v114 offset:1536
	ds_read_b128 v[76:79], v114 offset:1280
	ds_read_b128 v[88:91], v114 offset:2048
	ds_read_b128 v[84:87], v114 offset:1792
	s_waitcnt lgkmcnt(8)
	v_pk_mul_f32 v[58:59], v[44:45], v[2:3]
	s_waitcnt lgkmcnt(7)
	v_pk_mul_f32 v[60:61], v[40:41], v[2:3]
	v_pk_fma_f32 v[58:59], v[46:47], v[4:5], v[58:59]
	v_pk_mul_f32 v[62:63], v[42:43], v[4:5]
	v_add_f32_e32 v64, v58, v59
	s_waitcnt lgkmcnt(5)
	v_pk_fma_f32 v[60:61], v[52:53], v[120:121], v[60:61] op_sel_hi:[1,0,1]
	v_pk_fma_f32 v[62:63], v[54:55], v[120:121], v[62:63] op_sel_hi:[1,0,1]
	v_add_f32_dpp v65, v64, v64 quad_perm:[1,0,3,2] row_mask:0xf bank_mask:0xf bound_ctrl:1
	ds_read_b128 v[100:103], v114 offset:2816
	ds_read_b128 v[96:99], v114 offset:2560
	v_add_f32_dpp v64, v65, v65 quad_perm:[2,3,0,1] row_mask:0xf bank_mask:0xf bound_ctrl:1
	ds_read_b128 v[108:111], v114 offset:3328
	ds_read_b128 v[104:107], v114 offset:3072
	v_add_f32_dpp v65, v64, v64 row_half_mirror row_mask:0xf bank_mask:0xf bound_ctrl:1
	s_nop 0
	s_nop 0
	v_add_f32_dpp v66, v65, v65 row_mirror row_mask:0xf bank_mask:0xf bound_ctrl:1
	s_waitcnt lgkmcnt(8)
	v_pk_fma_f32 v[2:3], v[48:49], v[66:67], v[60:61] op_sel_hi:[1,0,1]
	v_pk_fma_f32 v[4:5], v[50:51], v[66:67], v[62:63] op_sel_hi:[1,0,1]
	s_waitcnt lgkmcnt(4)
	v_pk_mul_f32 v[58:59], v[80:81], v[2:3]
	v_pk_mul_f32 v[60:61], v[76:77], v[2:3]
	v_pk_fma_f32 v[58:59], v[82:83], v[4:5], v[58:59]
	v_pk_mul_f32 v[62:63], v[78:79], v[4:5]
	v_add_f32_e32 v64, v58, v59
	v_pk_fma_f32 v[60:61], v[88:89], v[120:121], v[60:61] op_sel:[0,1,0]
	v_pk_fma_f32 v[62:63], v[90:91], v[120:121], v[62:63] op_sel:[0,1,0]
	v_add_f32_dpp v65, v64, v64 quad_perm:[1,0,3,2] row_mask:0xf bank_mask:0xf bound_ctrl:1
	v_cvt_pk_bf16_f32 v68, v2, v3
	v_cvt_pk_bf16_f32 v69, v4, v5
	v_add_f32_dpp v64, v65, v65 quad_perm:[2,3,0,1] row_mask:0xf bank_mask:0xf bound_ctrl:1
	ds_write_b64 v116, v[68:69] offset:45056
	ds_read_b128 v[44:47], v114 offset:4096
	v_add_f32_dpp v65, v64, v64 row_half_mirror row_mask:0xf bank_mask:0xf bound_ctrl:1
	ds_read_b128 v[40:43], v114 offset:3840
	ds_read_b128 v[52:55], v114 offset:4608
	v_add_f32_dpp v66, v65, v65 row_mirror row_mask:0xf bank_mask:0xf bound_ctrl:1
	v_pk_fma_f32 v[2:3], v[84:85], v[66:67], v[60:61] op_sel_hi:[1,0,1]
	v_pk_fma_f32 v[4:5], v[86:87], v[66:67], v[62:63] op_sel_hi:[1,0,1]
	ds_read_b128 v[48:51], v114 offset:4352
	s_waitcnt lgkmcnt(5)
	v_pk_mul_f32 v[58:59], v[100:101], v[2:3]
	v_pk_mul_f32 v[60:61], v[96:97], v[2:3]
	v_pk_fma_f32 v[58:59], v[102:103], v[4:5], v[58:59]
	v_pk_mul_f32 v[62:63], v[98:99], v[4:5]
	v_add_f32_e32 v64, v58, v59
	v_pk_fma_f32 v[60:61], v[108:109], v[122:123], v[60:61] op_sel_hi:[1,0,1]
	v_pk_fma_f32 v[62:63], v[110:111], v[122:123], v[62:63] op_sel_hi:[1,0,1]
	v_add_f32_dpp v65, v64, v64 quad_perm:[1,0,3,2] row_mask:0xf bank_mask:0xf bound_ctrl:1
	v_cvt_pk_bf16_f32 v70, v2, v3
	v_cvt_pk_bf16_f32 v71, v4, v5
	v_add_f32_dpp v64, v65, v65 quad_perm:[2,3,0,1] row_mask:0xf bank_mask:0xf bound_ctrl:1
	ds_write_b64 v116, v[70:71] offset:47360
	ds_read_b128 v[80:83], v114 offset:5376
	v_add_f32_dpp v65, v64, v64 row_half_mirror row_mask:0xf bank_mask:0xf bound_ctrl:1
	ds_read_b128 v[76:79], v114 offset:5120
	ds_read_b128 v[88:91], v114 offset:5888
	v_add_f32_dpp v66, v65, v65 row_mirror row_mask:0xf bank_mask:0xf bound_ctrl:1
	v_pk_fma_f32 v[2:3], v[104:105], v[66:67], v[60:61] op_sel_hi:[1,0,1]
	v_pk_fma_f32 v[4:5], v[106:107], v[66:67], v[62:63] op_sel_hi:[1,0,1]
	ds_read_b128 v[124:127], v135 offset:1024
	ds_read_b128 v[84:87], v114 offset:5632
	s_waitcnt lgkmcnt(6)
	v_pk_mul_f32 v[58:59], v[44:45], v[2:3]
	v_pk_mul_f32 v[60:61], v[40:41], v[2:3]
	v_pk_fma_f32 v[58:59], v[46:47], v[4:5], v[58:59]
	v_pk_mul_f32 v[62:63], v[42:43], v[4:5]
	v_add_f32_e32 v64, v58, v59
	v_pk_fma_f32 v[60:61], v[52:53], v[122:123], v[60:61] op_sel:[0,1,0]
	v_pk_fma_f32 v[62:63], v[54:55], v[122:123], v[62:63] op_sel:[0,1,0]
	v_add_f32_dpp v65, v64, v64 quad_perm:[1,0,3,2] row_mask:0xf bank_mask:0xf bound_ctrl:1
	v_cvt_pk_bf16_f32 v68, v2, v3
	v_cvt_pk_bf16_f32 v69, v4, v5
	v_add_f32_dpp v64, v65, v65 quad_perm:[2,3,0,1] row_mask:0xf bank_mask:0xf bound_ctrl:1
	ds_write_b64 v116, v[68:69] offset:49664
	ds_read_b128 v[100:103], v114 offset:6656
	v_add_f32_dpp v65, v64, v64 row_half_mirror row_mask:0xf bank_mask:0xf bound_ctrl:1
	ds_read_b128 v[96:99], v114 offset:6400
	ds_read_b128 v[108:111], v114 offset:7168
	v_add_f32_dpp v66, v65, v65 row_mirror row_mask:0xf bank_mask:0xf bound_ctrl:1
	v_pk_fma_f32 v[2:3], v[48:49], v[66:67], v[60:61] op_sel_hi:[1,0,1]
	v_pk_fma_f32 v[4:5], v[50:51], v[66:67], v[62:63] op_sel_hi:[1,0,1]
	ds_read_b128 v[104:107], v114 offset:6912
	s_waitcnt lgkmcnt(5)
	v_pk_mul_f32 v[58:59], v[80:81], v[2:3]
	v_pk_mul_f32 v[60:61], v[76:77], v[2:3]
	v_pk_fma_f32 v[58:59], v[82:83], v[4:5], v[58:59]
	v_pk_mul_f32 v[62:63], v[78:79], v[4:5]
	v_add_f32_e32 v64, v58, v59
	v_pk_fma_f32 v[60:61], v[88:89], v[124:125], v[60:61] op_sel_hi:[1,0,1]
	v_pk_fma_f32 v[62:63], v[90:91], v[124:125], v[62:63] op_sel_hi:[1,0,1]
	v_add_f32_dpp v65, v64, v64 quad_perm:[1,0,3,2] row_mask:0xf bank_mask:0xf bound_ctrl:1
	v_cvt_pk_bf16_f32 v70, v2, v3
	v_cvt_pk_bf16_f32 v71, v4, v5
	v_add_f32_dpp v64, v65, v65 quad_perm:[2,3,0,1] row_mask:0xf bank_mask:0xf bound_ctrl:1
	ds_write_b64 v116, v[70:71] offset:51968
	ds_read_b128 v[44:47], v114 offset:7936
	v_add_f32_dpp v65, v64, v64 row_half_mirror row_mask:0xf bank_mask:0xf bound_ctrl:1
	ds_read_b128 v[40:43], v114 offset:7680
	ds_read_b128 v[52:55], v114 offset:8448
	v_add_f32_dpp v66, v65, v65 row_mirror row_mask:0xf bank_mask:0xf bound_ctrl:1
	v_pk_fma_f32 v[2:3], v[84:85], v[66:67], v[60:61] op_sel_hi:[1,0,1]
	v_pk_fma_f32 v[4:5], v[86:87], v[66:67], v[62:63] op_sel_hi:[1,0,1]
	ds_read_b128 v[48:51], v114 offset:8192
	s_waitcnt lgkmcnt(5)
	v_pk_mul_f32 v[58:59], v[100:101], v[2:3]
	v_pk_mul_f32 v[60:61], v[96:97], v[2:3]
	v_pk_fma_f32 v[58:59], v[102:103], v[4:5], v[58:59]
	v_pk_mul_f32 v[62:63], v[98:99], v[4:5]
	v_add_f32_e32 v64, v58, v59
	v_pk_fma_f32 v[60:61], v[108:109], v[124:125], v[60:61] op_sel:[0,1,0]
	v_pk_fma_f32 v[62:63], v[110:111], v[124:125], v[62:63] op_sel:[0,1,0]
	v_add_f32_dpp v65, v64, v64 quad_perm:[1,0,3,2] row_mask:0xf bank_mask:0xf bound_ctrl:1
	v_cvt_pk_bf16_f32 v68, v2, v3
	v_cvt_pk_bf16_f32 v69, v4, v5
	v_add_f32_dpp v64, v65, v65 quad_perm:[2,3,0,1] row_mask:0xf bank_mask:0xf bound_ctrl:1
	ds_write_b64 v116, v[68:69] offset:54272
	ds_read_b128 v[80:83], v114 offset:9216
	v_add_f32_dpp v65, v64, v64 row_half_mirror row_mask:0xf bank_mask:0xf bound_ctrl:1
	ds_read_b128 v[76:79], v114 offset:8960
	ds_read_b128 v[88:91], v114 offset:9728
	v_add_f32_dpp v66, v65, v65 row_mirror row_mask:0xf bank_mask:0xf bound_ctrl:1
	v_pk_fma_f32 v[2:3], v[104:105], v[66:67], v[60:61] op_sel_hi:[1,0,1]
	v_pk_fma_f32 v[4:5], v[106:107], v[66:67], v[62:63] op_sel_hi:[1,0,1]
	ds_read_b128 v[84:87], v114 offset:9472
	s_waitcnt lgkmcnt(5)
	v_pk_mul_f32 v[58:59], v[44:45], v[2:3]
	v_pk_mul_f32 v[60:61], v[40:41], v[2:3]
	v_pk_fma_f32 v[58:59], v[46:47], v[4:5], v[58:59]
	v_pk_mul_f32 v[62:63], v[42:43], v[4:5]
	v_add_f32_e32 v64, v58, v59
	v_pk_fma_f32 v[60:61], v[52:53], v[126:127], v[60:61] op_sel_hi:[1,0,1]
	v_pk_fma_f32 v[62:63], v[54:55], v[126:127], v[62:63] op_sel_hi:[1,0,1]
	v_add_f32_dpp v65, v64, v64 quad_perm:[1,0,3,2] row_mask:0xf bank_mask:0xf bound_ctrl:1
	v_cvt_pk_bf16_f32 v70, v2, v3
	v_cvt_pk_bf16_f32 v71, v4, v5
	v_add_f32_dpp v64, v65, v65 quad_perm:[2,3,0,1] row_mask:0xf bank_mask:0xf bound_ctrl:1
	ds_write_b64 v116, v[70:71] offset:56576
	ds_read_b128 v[100:103], v114 offset:10496
	v_add_f32_dpp v65, v64, v64 row_half_mirror row_mask:0xf bank_mask:0xf bound_ctrl:1
	ds_read_b128 v[96:99], v114 offset:10240
	ds_read_b128 v[108:111], v114 offset:11008
	v_add_f32_dpp v66, v65, v65 row_mirror row_mask:0xf bank_mask:0xf bound_ctrl:1
	v_pk_fma_f32 v[2:3], v[48:49], v[66:67], v[60:61] op_sel_hi:[1,0,1]
	v_pk_fma_f32 v[4:5], v[50:51], v[66:67], v[62:63] op_sel_hi:[1,0,1]
	ds_read_b128 v[128:131], v135 offset:2048
	ds_read_b128 v[104:107], v114 offset:10752
	s_waitcnt lgkmcnt(6)
	v_pk_mul_f32 v[58:59], v[80:81], v[2:3]
	v_pk_mul_f32 v[60:61], v[76:77], v[2:3]
	v_pk_fma_f32 v[58:59], v[82:83], v[4:5], v[58:59]
	v_pk_mul_f32 v[62:63], v[78:79], v[4:5]
	v_add_f32_e32 v64, v58, v59
	v_pk_fma_f32 v[60:61], v[88:89], v[126:127], v[60:61] op_sel:[0,1,0]
	v_pk_fma_f32 v[62:63], v[90:91], v[126:127], v[62:63] op_sel:[0,1,0]
	v_add_f32_dpp v65, v64, v64 quad_perm:[1,0,3,2] row_mask:0xf bank_mask:0xf bound_ctrl:1
	v_cvt_pk_bf16_f32 v68, v2, v3
	v_cvt_pk_bf16_f32 v69, v4, v5
	v_add_f32_dpp v64, v65, v65 quad_perm:[2,3,0,1] row_mask:0xf bank_mask:0xf bound_ctrl:1
	ds_write_b64 v116, v[68:69] offset:58880
	ds_read_b128 v[44:47], v114 offset:11776
	v_add_f32_dpp v65, v64, v64 row_half_mirror row_mask:0xf bank_mask:0xf bound_ctrl:1
	ds_read_b128 v[40:43], v114 offset:11520
	ds_read_b128 v[52:55], v114 offset:12288
	v_add_f32_dpp v66, v65, v65 row_mirror row_mask:0xf bank_mask:0xf bound_ctrl:1
	v_pk_fma_f32 v[2:3], v[84:85], v[66:67], v[60:61] op_sel_hi:[1,0,1]
	v_pk_fma_f32 v[4:5], v[86:87], v[66:67], v[62:63] op_sel_hi:[1,0,1]
	ds_read_b128 v[48:51], v114 offset:12032
	s_waitcnt lgkmcnt(5)
	v_pk_mul_f32 v[58:59], v[100:101], v[2:3]
	v_pk_mul_f32 v[60:61], v[96:97], v[2:3]
	v_pk_fma_f32 v[58:59], v[102:103], v[4:5], v[58:59]
	v_pk_mul_f32 v[62:63], v[98:99], v[4:5]
	v_add_f32_e32 v64, v58, v59
	v_pk_fma_f32 v[60:61], v[108:109], v[128:129], v[60:61] op_sel_hi:[1,0,1]
	v_pk_fma_f32 v[62:63], v[110:111], v[128:129], v[62:63] op_sel_hi:[1,0,1]
	v_add_f32_dpp v65, v64, v64 quad_perm:[1,0,3,2] row_mask:0xf bank_mask:0xf bound_ctrl:1
	v_cvt_pk_bf16_f32 v70, v2, v3
	v_cvt_pk_bf16_f32 v71, v4, v5
	v_add_f32_dpp v64, v65, v65 quad_perm:[2,3,0,1] row_mask:0xf bank_mask:0xf bound_ctrl:1
	ds_write_b64 v116, v[70:71] offset:61184
	ds_read_b128 v[80:83], v114 offset:13056
	v_add_f32_dpp v65, v64, v64 row_half_mirror row_mask:0xf bank_mask:0xf bound_ctrl:1
	ds_read_b128 v[76:79], v114 offset:12800
	ds_read_b128 v[88:91], v114 offset:13568
	v_add_f32_dpp v66, v65, v65 row_mirror row_mask:0xf bank_mask:0xf bound_ctrl:1
	v_pk_fma_f32 v[2:3], v[104:105], v[66:67], v[60:61] op_sel_hi:[1,0,1]
	v_pk_fma_f32 v[4:5], v[106:107], v[66:67], v[62:63] op_sel_hi:[1,0,1]
	ds_read_b128 v[84:87], v114 offset:13312
	s_waitcnt lgkmcnt(5)
	v_pk_mul_f32 v[58:59], v[44:45], v[2:3]
	v_pk_mul_f32 v[60:61], v[40:41], v[2:3]
	v_pk_fma_f32 v[58:59], v[46:47], v[4:5], v[58:59]
	v_pk_mul_f32 v[62:63], v[42:43], v[4:5]
	v_add_f32_e32 v64, v58, v59
	v_pk_fma_f32 v[60:61], v[52:53], v[128:129], v[60:61] op_sel:[0,1,0]
	v_pk_fma_f32 v[62:63], v[54:55], v[128:129], v[62:63] op_sel:[0,1,0]
	v_add_f32_dpp v65, v64, v64 quad_perm:[1,0,3,2] row_mask:0xf bank_mask:0xf bound_ctrl:1
	v_cvt_pk_bf16_f32 v68, v2, v3
	v_cvt_pk_bf16_f32 v69, v4, v5
	v_add_f32_dpp v64, v65, v65 quad_perm:[2,3,0,1] row_mask:0xf bank_mask:0xf bound_ctrl:1
	ds_write_b64 v116, v[68:69] offset:63488
	ds_read_b128 v[100:103], v114 offset:14336
	v_add_f32_dpp v65, v64, v64 row_half_mirror row_mask:0xf bank_mask:0xf bound_ctrl:1
	ds_read_b128 v[96:99], v114 offset:14080
	ds_read_b128 v[108:111], v114 offset:14848
	v_add_f32_dpp v66, v65, v65 row_mirror row_mask:0xf bank_mask:0xf bound_ctrl:1
	v_pk_fma_f32 v[2:3], v[48:49], v[66:67], v[60:61] op_sel_hi:[1,0,1]
	v_pk_fma_f32 v[4:5], v[50:51], v[66:67], v[62:63] op_sel_hi:[1,0,1]
	ds_read_b128 v[104:107], v114 offset:14592
	s_waitcnt lgkmcnt(5)
	v_pk_mul_f32 v[58:59], v[80:81], v[2:3]
	v_pk_mul_f32 v[60:61], v[76:77], v[2:3]
	v_pk_fma_f32 v[58:59], v[82:83], v[4:5], v[58:59]
	v_pk_mul_f32 v[62:63], v[78:79], v[4:5]
	v_add_f32_e32 v64, v58, v59
	v_pk_fma_f32 v[60:61], v[88:89], v[130:131], v[60:61] op_sel_hi:[1,0,1]
	v_pk_fma_f32 v[62:63], v[90:91], v[130:131], v[62:63] op_sel_hi:[1,0,1]
	v_add_f32_dpp v65, v64, v64 quad_perm:[1,0,3,2] row_mask:0xf bank_mask:0xf bound_ctrl:1
	v_cvt_pk_bf16_f32 v70, v2, v3
	v_cvt_pk_bf16_f32 v71, v4, v5
	v_add_f32_dpp v64, v65, v65 quad_perm:[2,3,0,1] row_mask:0xf bank_mask:0xf bound_ctrl:1
	ds_write_b64 v117, v[70:71] offset:20736
	ds_read_b128 v[44:47], v114 offset:15616
	v_add_f32_dpp v65, v64, v64 row_half_mirror row_mask:0xf bank_mask:0xf bound_ctrl:1
	ds_read_b128 v[40:43], v114 offset:15360
	ds_read_b128 v[52:55], v114 offset:16128
	v_add_f32_dpp v66, v65, v65 row_mirror row_mask:0xf bank_mask:0xf bound_ctrl:1
	v_pk_fma_f32 v[2:3], v[84:85], v[66:67], v[60:61] op_sel_hi:[1,0,1]
	v_pk_fma_f32 v[4:5], v[86:87], v[66:67], v[62:63] op_sel_hi:[1,0,1]
	ds_read_b128 v[136:139], v135 offset:3072
	ds_read_b128 v[48:51], v114 offset:15872
	s_waitcnt lgkmcnt(6)
	v_pk_mul_f32 v[58:59], v[100:101], v[2:3]
	v_pk_mul_f32 v[60:61], v[96:97], v[2:3]
	v_pk_fma_f32 v[58:59], v[102:103], v[4:5], v[58:59]
	v_pk_mul_f32 v[62:63], v[98:99], v[4:5]
	v_add_f32_e32 v64, v58, v59
	v_pk_fma_f32 v[60:61], v[108:109], v[130:131], v[60:61] op_sel:[0,1,0]
	v_pk_fma_f32 v[62:63], v[110:111], v[130:131], v[62:63] op_sel:[0,1,0]
	v_add_f32_dpp v65, v64, v64 quad_perm:[1,0,3,2] row_mask:0xf bank_mask:0xf bound_ctrl:1
	v_cvt_pk_bf16_f32 v68, v2, v3
	v_cvt_pk_bf16_f32 v69, v4, v5
	v_add_f32_dpp v64, v65, v65 quad_perm:[2,3,0,1] row_mask:0xf bank_mask:0xf bound_ctrl:1
	ds_write_b64 v117, v[68:69] offset:23040
	ds_read_b128 v[80:83], v114 offset:16896
	v_add_f32_dpp v65, v64, v64 row_half_mirror row_mask:0xf bank_mask:0xf bound_ctrl:1
	ds_read_b128 v[76:79], v114 offset:16640
	ds_read_b128 v[88:91], v114 offset:17408
	v_add_f32_dpp v66, v65, v65 row_mirror row_mask:0xf bank_mask:0xf bound_ctrl:1
	v_pk_fma_f32 v[2:3], v[104:105], v[66:67], v[60:61] op_sel_hi:[1,0,1]
	v_pk_fma_f32 v[4:5], v[106:107], v[66:67], v[62:63] op_sel_hi:[1,0,1]
	ds_read_b128 v[84:87], v114 offset:17152
	s_waitcnt lgkmcnt(5)
	v_pk_mul_f32 v[58:59], v[44:45], v[2:3]
	v_pk_mul_f32 v[60:61], v[40:41], v[2:3]
	v_pk_fma_f32 v[58:59], v[46:47], v[4:5], v[58:59]
	v_pk_mul_f32 v[62:63], v[42:43], v[4:5]
	v_add_f32_e32 v64, v58, v59
	v_pk_fma_f32 v[60:61], v[52:53], v[136:137], v[60:61] op_sel_hi:[1,0,1]
	v_pk_fma_f32 v[62:63], v[54:55], v[136:137], v[62:63] op_sel_hi:[1,0,1]
	v_add_f32_dpp v65, v64, v64 quad_perm:[1,0,3,2] row_mask:0xf bank_mask:0xf bound_ctrl:1
	v_cvt_pk_bf16_f32 v70, v2, v3
	v_cvt_pk_bf16_f32 v71, v4, v5
	v_add_f32_dpp v64, v65, v65 quad_perm:[2,3,0,1] row_mask:0xf bank_mask:0xf bound_ctrl:1
	ds_write_b64 v117, v[70:71] offset:25344
	ds_read_b128 v[100:103], v114 offset:18176
	v_add_f32_dpp v65, v64, v64 row_half_mirror row_mask:0xf bank_mask:0xf bound_ctrl:1
	ds_read_b128 v[96:99], v114 offset:17920
	ds_read_b128 v[108:111], v114 offset:18688
	v_add_f32_dpp v66, v65, v65 row_mirror row_mask:0xf bank_mask:0xf bound_ctrl:1
	v_pk_fma_f32 v[2:3], v[48:49], v[66:67], v[60:61] op_sel_hi:[1,0,1]
	v_pk_fma_f32 v[4:5], v[50:51], v[66:67], v[62:63] op_sel_hi:[1,0,1]
	ds_read_b128 v[104:107], v114 offset:18432
	s_waitcnt lgkmcnt(5)
	v_pk_mul_f32 v[58:59], v[80:81], v[2:3]
	v_pk_mul_f32 v[60:61], v[76:77], v[2:3]
	v_pk_fma_f32 v[58:59], v[82:83], v[4:5], v[58:59]
	v_pk_mul_f32 v[62:63], v[78:79], v[4:5]
	v_add_f32_e32 v64, v58, v59
	v_pk_fma_f32 v[60:61], v[88:89], v[136:137], v[60:61] op_sel:[0,1,0]
	v_pk_fma_f32 v[62:63], v[90:91], v[136:137], v[62:63] op_sel:[0,1,0]
	v_add_f32_dpp v65, v64, v64 quad_perm:[1,0,3,2] row_mask:0xf bank_mask:0xf bound_ctrl:1
	v_cvt_pk_bf16_f32 v68, v2, v3
	v_cvt_pk_bf16_f32 v69, v4, v5
	v_add_f32_dpp v64, v65, v65 quad_perm:[2,3,0,1] row_mask:0xf bank_mask:0xf bound_ctrl:1
	ds_write_b64 v117, v[68:69] offset:27648
	ds_read_b128 v[44:47], v114 offset:19456
	v_add_f32_dpp v65, v64, v64 row_half_mirror row_mask:0xf bank_mask:0xf bound_ctrl:1
	ds_read_b128 v[40:43], v114 offset:19200
	ds_read_b128 v[52:55], v114 offset:19968
	v_add_f32_dpp v66, v65, v65 row_mirror row_mask:0xf bank_mask:0xf bound_ctrl:1
	v_pk_fma_f32 v[2:3], v[84:85], v[66:67], v[60:61] op_sel_hi:[1,0,1]
	v_pk_fma_f32 v[4:5], v[86:87], v[66:67], v[62:63] op_sel_hi:[1,0,1]
	ds_read_b128 v[48:51], v114 offset:19712
	s_waitcnt lgkmcnt(5)
	v_pk_mul_f32 v[58:59], v[100:101], v[2:3]
	v_pk_mul_f32 v[60:61], v[96:97], v[2:3]
	v_pk_fma_f32 v[58:59], v[102:103], v[4:5], v[58:59]
	v_pk_mul_f32 v[62:63], v[98:99], v[4:5]
	v_add_f32_e32 v64, v58, v59
	v_pk_fma_f32 v[60:61], v[108:109], v[138:139], v[60:61] op_sel_hi:[1,0,1]
	v_pk_fma_f32 v[62:63], v[110:111], v[138:139], v[62:63] op_sel_hi:[1,0,1]
	v_add_f32_dpp v65, v64, v64 quad_perm:[1,0,3,2] row_mask:0xf bank_mask:0xf bound_ctrl:1
	v_cvt_pk_bf16_f32 v70, v2, v3
	v_cvt_pk_bf16_f32 v71, v4, v5
	v_add_f32_dpp v64, v65, v65 quad_perm:[2,3,0,1] row_mask:0xf bank_mask:0xf bound_ctrl:1
	ds_write_b64 v117, v[70:71] offset:29952
	s_nop 0
	v_add_f32_dpp v65, v64, v64 row_half_mirror row_mask:0xf bank_mask:0xf bound_ctrl:1
	s_nop 0
	s_nop 0
	v_add_f32_dpp v66, v65, v65 row_mirror row_mask:0xf bank_mask:0xf bound_ctrl:1
	v_pk_fma_f32 v[2:3], v[104:105], v[66:67], v[60:61] op_sel_hi:[1,0,1]
	v_pk_fma_f32 v[4:5], v[106:107], v[66:67], v[62:63] op_sel_hi:[1,0,1]
	s_waitcnt lgkmcnt(1)
	v_pk_mul_f32 v[58:59], v[44:45], v[2:3]
	v_pk_mul_f32 v[60:61], v[40:41], v[2:3]
	v_pk_fma_f32 v[58:59], v[46:47], v[4:5], v[58:59]
	v_pk_mul_f32 v[62:63], v[42:43], v[4:5]
	v_add_f32_e32 v64, v58, v59
	v_pk_fma_f32 v[60:61], v[52:53], v[138:139], v[60:61] op_sel:[0,1,0]
	v_pk_fma_f32 v[62:63], v[54:55], v[138:139], v[62:63] op_sel:[0,1,0]
	v_add_f32_dpp v65, v64, v64 quad_perm:[1,0,3,2] row_mask:0xf bank_mask:0xf bound_ctrl:1
	v_cvt_pk_bf16_f32 v68, v2, v3
	v_cvt_pk_bf16_f32 v69, v4, v5
	v_add_f32_dpp v64, v65, v65 quad_perm:[2,3,0,1] row_mask:0xf bank_mask:0xf bound_ctrl:1
	ds_write_b64 v117, v[68:69] offset:32256
	s_nop 0
	v_add_f32_dpp v65, v64, v64 row_half_mirror row_mask:0xf bank_mask:0xf bound_ctrl:1
	s_nop 0
	s_nop 0
	v_add_f32_dpp v66, v65, v65 row_mirror row_mask:0xf bank_mask:0xf bound_ctrl:1
	v_pk_fma_f32 v[2:3], v[48:49], v[66:67], v[60:61] op_sel_hi:[1,0,1]
	v_pk_fma_f32 v[4:5], v[50:51], v[66:67], v[62:63] op_sel_hi:[1,0,1]
	v_cvt_pk_bf16_f32 v70, v2, v3
	v_cvt_pk_bf16_f32 v71, v4, v5
	ds_write_b64 v117, v[70:71] offset:34560
	s_add_i32 s0, s0, 1
	s_waitcnt lgkmcnt(0)
	s_barrier
	s_branch .LBB0_1047

.LBB0_1049:
	s_and_b64 vcc, exec, s[0:1]
	s_cbranch_vccz .LBB0_1102
	s_ashr_i32 s0, s2, 5
	s_bfe_u32 s7, s2, 0x30002
	v_lshlrev_b32_e32 v2, 2, v169
	s_ashr_i32 s1, s0, 31
	s_mul_i32 s10, s0, 0x1c8e400
	v_lshl_or_b32 v28, s7, 6, v2
	v_mov_b32_e32 v29, 0
	s_mul_hi_i32 s11, s0, 0x1c8e400
	s_add_u32 s10, s38, s10
	v_lshlrev_b64 v[6:7], 2, v[28:29]
	s_addc_u32 s11, s39, s11
	v_lshlrev_b32_e32 v28, 1, v28
	v_lshl_add_u64 v[30:31], s[10:11], 0, v[28:29]
	s_mul_i32 s11, s0, 0x804000
	s_mul_hi_i32 s10, s0, 0x804000
	s_add_u32 s4, s4, s11
	s_addc_u32 s5, s5, s10
	v_lshl_add_u64 v[32:33], s[4:5], 0, v[28:29]
	s_add_u32 s4, s16, s11
	s_addc_u32 s5, s17, s10
	v_lshl_add_u64 v[34:35], s[4:5], 0, v[28:29]
	s_mul_i32 s5, s0, 0x40200
	s_mul_hi_i32 s4, s0, 0x40200
	s_add_u32 s5, s28, s5
	s_addc_u32 s4, s29, s4
	s_lshl_b32 s10, s7, 2
	s_add_u32 s5, s5, s10
	s_addc_u32 s4, s4, 0
	s_add_u32 s36, s5, 0xfd30000
	s_addc_u32 s37, s4, 0
	s_lshl_b64 s[0:1], s[0:1], 23
	s_add_u32 s0, s44, s0
	s_addc_u32 s1, s45, s1
	s_lshl_b32 s4, s7, 7
	s_add_u32 s0, s0, s4
	s_addc_u32 s1, s1, 0
	s_lshl_b32 s4, s6, 5
	s_add_u32 s0, s0, s4
	s_addc_u32 s1, s1, 0
	s_add_u32 s40, s28, 0xfdf3f00
	v_readlane_b32 s4, v255, 5
	s_addc_u32 s41, s29, 0
	s_lshl_b32 s35, s4, 2
	v_lshlrev_b32_e32 v28, 3, v166
	s_add_i32 s62, s35, -16
	v_lshl_add_u64 v[26:27], s[0:1], 0, v[28:29]
	v_or_b32_e32 v28, s62, v166
	s_movk_i32 s63, 0xe40
	v_mad_u64_u32 v[2:3], s[0:1], v28, s63, v[30:31]
	v_max_i32_e32 v4, 1, v28
	global_load_dwordx2 v[24:25], v[2:3], off
	global_load_dwordx2 v[50:51], v[2:3], off offset:1024
	global_load_dwordx2 v[52:53], v[2:3], off offset:2048
	v_add_u32_e32 v2, -1, v4
	v_mad_u64_u32 v[2:3], s[0:1], v2, s63, v[30:31]
	v_readlane_b32 s64, v255, 7
	global_load_dwordx2 v[54:55], v[2:3], off
	global_load_dwordx2 v[56:57], v[2:3], off offset:1024
	global_load_dwordx2 v[58:59], v[2:3], off offset:2048
	v_lshlrev_b64 v[2:3], 10, v[28:29]
	v_readlane_b32 s78, v255, 21
	v_readlane_b32 s79, v255, 22
	v_lshl_add_u64 v[4:5], v[32:33], 0, v[2:3]
	v_lshl_add_u64 v[2:3], v[34:35], 0, v[2:3]
	v_lshl_add_u64 v[18:19], s[78:79], 0, v[6:7]
	global_load_dwordx2 v[60:61], v[4:5], off
	global_load_dwordx2 v[62:63], v[2:3], off
	v_lshl_add_u64 v[10:11], s[46:47], 0, v[6:7]
	global_load_dwordx4 v[2:5], v[18:19], off
	v_lshl_add_u64 v[14:15], s[48:49], 0, v[6:7]
	global_load_dwordx4 v[6:9], v[18:19], off offset:2048
	v_add_co_u32_e32 v18, vcc, 0x1000, v18
	global_load_dwordx4 v[10:13], v[10:11], off
	s_nop 0
	global_load_dwordx4 v[14:17], v[14:15], off
	v_addc_co_u32_e32 v19, vcc, 0, v19, vcc
	global_load_dwordx4 v[18:21], v[18:19], off
	v_or_b32_e32 v36, s35, v166
	v_add_u32_e32 v23, -1, v36
	v_cmp_eq_u32_e32 vcc, 0, v28
	v_mov_b32_e32 v37, v29
	v_mad_u64_u32 v[42:43], s[0:1], v36, s63, v[30:31]
	v_mad_u64_u32 v[46:47], s[0:1], v23, s63, v[30:31]
	v_cndmask_b32_e64 v72, 1.0, 0, vcc
	v_lshlrev_b64 v[38:39], 10, v[36:37]
	v_lshlrev_b64 v[40:41], 5, v[28:29]
	s_add_i32 s0, s35, 16
	v_lshlrev_b64 v[36:37], 5, v[36:37]
	v_lshl_add_u64 v[48:49], v[32:33], 0, v[38:39]
	v_lshl_add_u64 v[64:65], v[34:35], 0, v[38:39]
	v_lshl_add_u64 v[38:39], s[36:37], 0, v[40:41]
	v_lshl_add_u64 v[66:67], s[36:37], 0, v[36:37]
	global_load_dwordx2 v[36:37], v[46:47], off
	global_load_dwordx2 v[44:45], v[46:47], off offset:1024
	s_nop 0
	global_load_dwordx2 v[46:47], v[46:47], off offset:2048
	s_nop 0
	global_load_dwordx2 v[48:49], v[48:49], off
	s_nop 0
	global_load_dword v86, v[38:39], off
	s_nop 0
	global_load_dwordx2 v[38:39], v[42:43], off
	global_load_dwordx2 v[40:41], v[42:43], off offset:1024
	s_nop 0
	global_load_dwordx2 v[42:43], v[42:43], off offset:2048
	s_cmp_eq_u32 s4, 4
	v_readlane_b32 s69, v255, 12
	s_cselect_b64 s[46:47], -1, 0
	v_readlane_b32 s70, v255, 13
	s_movk_i32 s6, 0x90
	s_add_i32 s69, s35, -15
	v_readlane_b32 s71, v255, 14
	s_add_i32 s70, s35, -14
	s_add_i32 s71, s35, -13
	v_readlane_b32 s65, v255, 8
	v_readlane_b32 s66, v255, 9
	v_readlane_b32 s67, v255, 10
	v_readlane_b32 s68, v255, 11
	v_readlane_b32 s72, v255, 15
	s_mov_b32 s57, 0
	v_cmp_eq_u32_e64 s[4:5], 0, v178
	s_sub_i32 s67, s3, 64
	s_lshl_b32 s68, s62, 7
	s_lshl_b32 s66, s69, 7
	s_lshl_b32 s65, s70, 7
	s_lshl_b32 s64, s71, 7
	s_mov_b32 s72, 0
	v_readlane_b32 s73, v255, 16
	v_readlane_b32 s74, v255, 17
	v_readlane_b32 s75, v255, 18
	v_readlane_b32 s76, v255, 19
	v_readlane_b32 s77, v255, 20
	s_waitcnt vmcnt(20)
	v_lshlrev_b32_e32 v68, 16, v24
	v_and_b32_e32 v69, 0xffff0000, v24
	s_waitcnt vmcnt(19)
	v_lshlrev_b32_e32 v74, 16, v50
	v_and_b32_e32 v75, 0xffff0000, v50
	v_lshlrev_b32_e32 v76, 16, v51
	v_and_b32_e32 v77, 0xffff0000, v51
	s_waitcnt vmcnt(18)
	v_lshlrev_b32_e32 v78, 16, v52
	v_and_b32_e32 v79, 0xffff0000, v52
	v_lshlrev_b32_e32 v80, 16, v53
	v_and_b32_e32 v81, 0xffff0000, v53
	s_waitcnt vmcnt(17)
	v_lshlrev_b32_e32 v50, 16, v54
	v_and_b32_e32 v51, 0xffff0000, v54
	v_lshlrev_b32_e32 v52, 16, v55
	v_and_b32_e32 v53, 0xffff0000, v55
	s_waitcnt vmcnt(16)
	v_lshlrev_b32_e32 v82, 16, v56
	v_and_b32_e32 v83, 0xffff0000, v56
	v_lshlrev_b32_e32 v54, 16, v57
	v_and_b32_e32 v55, 0xffff0000, v57
	v_xor_b32_e32 v57, 0x80000000, v69
	v_xor_b32_e32 v56, 0x80000000, v68
	v_lshlrev_b32_e32 v24, 16, v25
	v_and_b32_e32 v25, 0xffff0000, v25
	v_pk_fma_f32 v[50:51], v[72:73], v[50:51], v[56:57] op_sel_hi:[0,1,1]
	v_xor_b32_e32 v57, 0x80000000, v25
	v_xor_b32_e32 v56, 0x80000000, v24
	s_waitcnt vmcnt(12)
	v_pk_fma_f32 v[94:95], v[2:3], v[50:51], v[68:69]
	v_xor_b32_e32 v51, 0x80000000, v77
	v_xor_b32_e32 v50, 0x80000000, v76
	v_or_b32_e32 v68, s0, v166
	v_pk_fma_f32 v[52:53], v[72:73], v[52:53], v[56:57] op_sel_hi:[0,1,1]
	v_pk_fma_f32 v[96:97], v[72:73], v[54:55], v[50:51] op_sel_hi:[0,1,1]
	v_add_u32_e32 v50, -1, v68
	v_mad_u64_u32 v[54:55], s[0:1], v68, s63, v[30:31]
	v_lshlrev_b32_e32 v84, 16, v58
	v_and_b32_e32 v85, 0xffff0000, v58
	v_lshlrev_b32_e32 v88, 16, v59
	v_and_b32_e32 v89, 0xffff0000, v59
	v_lshlrev_b32_e32 v23, 16, v60
	v_and_b32_e32 v87, 0xffff0000, v60
	v_lshlrev_b32_e32 v104, 16, v61
	v_and_b32_e32 v105, 0xffff0000, v61
	v_lshlrev_b32_e32 v90, 16, v62
	v_and_b32_e32 v91, 0xffff0000, v62
	v_pk_fma_f32 v[24:25], v[4:5], v[52:53], v[24:25]
	v_mad_u64_u32 v[70:71], s[0:1], v50, s63, v[30:31]
	global_load_dwordx2 v[58:59], v[64:65], off
	global_load_dword v62, v[66:67], off
	global_load_dwordx2 v[50:51], v[54:55], off
	global_load_dwordx2 v[52:53], v[54:55], off offset:1024
	s_nop 0
	global_load_dwordx2 v[54:55], v[54:55], off offset:2048
	s_nop 0
	global_load_dwordx2 v[56:57], v[70:71], off
	global_load_dwordx2 v[60:61], v[70:71], off offset:1024
	global_load_dwordx2 v[64:65], v[70:71], off offset:2048
	v_mov_b32_e32 v69, v29
	v_lshlrev_b64 v[66:67], 10, v[68:69]
	v_lshl_add_u64 v[70:71], v[32:33], 0, v[66:67]
	v_lshl_add_u64 v[100:101], v[34:35], 0, v[66:67]
	v_lshlrev_b64 v[66:67], 5, v[68:69]
	v_lshl_add_u64 v[102:103], s[36:37], 0, v[66:67]
	global_load_dwordx2 v[66:67], v[70:71], off
	global_load_dwordx2 v[68:69], v[100:101], off
	s_nop 0
	global_load_dword v70, v[102:103], off
	v_xor_b32_e32 v99, 0x80000000, v75
	v_xor_b32_e32 v98, 0x80000000, v74
	v_pk_fma_f32 v[82:83], v[72:73], v[82:83], v[98:99] op_sel_hi:[0,1,1]
	v_mul_f32_e32 v23, 0xbfb8aa3b, v23
	s_waitcnt vmcnt(22)
	v_pk_fma_f32 v[98:99], v[6:7], v[82:83], v[74:75]
	v_exp_f32_e32 v82, v23
	v_mul_f32_e32 v23, 0xbfb8aa3b, v87
	v_xor_b32_e32 v75, 0x80000000, v79
	v_xor_b32_e32 v74, 0x80000000, v78
	v_exp_f32_e32 v83, v23
	v_mul_f32_e32 v23, 0xbfb8aa3b, v104
	v_pk_fma_f32 v[96:97], v[8:9], v[96:97], v[76:77]
	v_pk_fma_f32 v[74:75], v[72:73], v[84:85], v[74:75] op_sel_hi:[0,1,1]
	v_xor_b32_e32 v77, 0x80000000, v81
	v_xor_b32_e32 v76, 0x80000000, v80
	v_exp_f32_e32 v84, v23
	v_mul_f32_e32 v23, 0xbfb8aa3b, v105
	v_lshlrev_b32_e32 v92, 16, v63
	v_and_b32_e32 v93, 0xffff0000, v63
	v_pk_fma_f32 v[72:73], v[72:73], v[88:89], v[76:77] op_sel_hi:[0,1,1]
	v_exp_f32_e32 v85, v23
	s_movk_i32 s0, 0x500
	s_waitcnt vmcnt(19)
	v_pk_fma_f32 v[76:77], v[20:21], v[72:73], v[80:81]
	v_pk_add_f32 v[72:73], v[92:93], -1.0 op_sel_hi:[1,0]
	v_mul_lo_u32 v23, v28, s0
	v_pk_fma_f32 v[72:73], v[16:17], v[72:73], 1.0 op_sel_hi:[1,1,0]
	v_add_u32_e32 v23, 0, v23
	v_pk_mul_f32 v[80:81], v[96:97], v[72:73]
	v_lshl_add_u32 v73, v169, 4, v23
	s_lshl_b32 s99, s62, 8
	s_add_i32 s99, s99, 0x1d000
	v_lshl_add_u32 v118, v166, 2, s99
	v_add_u32_e32 v114, 0, v169
	v_and_b32_e32 v114, 15, v114
	v_lshl_add_u32 v114, v114, 4, v118
	v_add_u32_e32 v114, 0, v114
	v_add_u32_e32 v115, 4, v169
	v_and_b32_e32 v115, 15, v115
	v_lshl_add_u32 v115, v115, 4, v118
	v_add_u32_e32 v115, 256, v115
	v_add_u32_e32 v116, 8, v169
	v_and_b32_e32 v116, 15, v116
	v_lshl_add_u32 v116, v116, 4, v118
	v_add_u32_e32 v116, 512, v116
	v_add_u32_e32 v117, 12, v169
	v_and_b32_e32 v117, 15, v117
	v_lshl_add_u32 v117, v117, 4, v118
	v_add_u32_e32 v117, 768, v117
	ds_write_b128 v73, v[82:85]
	v_pk_mul_f32 v[82:83], v[12:13], v[96:97] neg_lo:[0,1] neg_hi:[0,1]
	v_pk_fma_f32 v[74:75], v[18:19], v[74:75], v[78:79]
	s_waitcnt vmcnt(14)
	v_pk_mul_f32 v[84:85], v[86:87], v[82:83] op_sel_hi:[0,1]
	v_pk_mul_f32 v[82:83], v[10:11], v[98:99] neg_lo:[0,1] neg_hi:[0,1]
	v_pk_add_f32 v[78:79], v[90:91], -1.0 op_sel_hi:[1,0]
	v_pk_mul_f32 v[82:83], v[86:87], v[82:83] op_sel_hi:[0,1]
	v_pk_fma_f32 v[78:79], v[14:15], v[78:79], 1.0 op_sel_hi:[1,1,0]
	ds_write_b128 v73, v[82:85] offset:256
	v_pk_mul_f32 v[84:85], v[84:85], v[92:93] neg_lo:[1,0] neg_hi:[1,0]
	v_pk_mul_f32 v[82:83], v[82:83], v[90:91] neg_lo:[1,0] neg_hi:[1,0]
	s_movk_i32 s0, 0xfb80
	v_pk_mul_f32 v[78:79], v[98:99], v[78:79]
	ds_write_b128 v73, v[82:85] offset:512
	ds_write_b128 v73, v[78:81] offset:768
	ds_write_b32 v114, v74
	ds_write_b32 v115, v75
	ds_write_b32 v116, v76
	ds_write_b32 v117, v77
	v_cvt_pk_bf16_f32 v77, v24, v25
	v_mul_lo_u32 v24, v28, s0
	v_cvt_pk_bf16_f32 v76, v94, v95
	v_add3_u32 v75, v23, v24, v22
	v_and_b32_e32 v22, 48, v0
	s_add_i32 s0, 0, 0x14000
	ds_write_b64 v75, v[76:77] offset:40960
	v_add_u32_e32 v76, s0, v22
	v_add_u32_e32 v63, 0, v22
	v_lshl_or_b32 v22, s62, 4, v169
	v_mul_lo_u32 v79, v22, s6
	v_lshl_or_b32 v22, s69, 4, v169
	v_mul_lo_u32 v74, v22, s6
	v_lshl_or_b32 v22, s70, 4, v169
	v_mul_lo_u32 v72, v22, s6
	v_lshl_or_b32 v22, s71, 4, v169
	v_cmp_eq_u32_e64 s[0:1], 0, v169
	v_add_u32_e32 v77, 48, v28
	v_or_b32_e32 v78, 64, v166
	v_mul_lo_u32 v71, v22, s6
	v_sub_u32_e32 v80, 0, v28
	v_add_u32_e32 v112, 4, v169
	v_and_b32_e32 v112, 8, v112
	v_lshlrev_b32_e32 v112, 1, v112
	v_xor_b32_e32 v113, v112, v76
	v_xor_b32_e32 v112, v112, v63
	v_add_u32_e32 v212, v113, v79
	v_add_u32_e32 v216, v112, v79
	v_add_u32_e32 v220, s68, v63
	v_add_u32_e32 v213, v113, v74
	v_add_u32_e32 v217, v112, v74
	v_add_u32_e32 v221, s66, v63
	v_add_u32_e32 v214, v113, v72
	v_add_u32_e32 v218, v112, v72
	v_add_u32_e32 v222, s65, v63
	v_add_u32_e32 v215, v113, v71
	v_add_u32_e32 v219, v112, v71
	v_add_u32_e32 v223, s64, v63
	s_waitcnt lgkmcnt(0)
	s_barrier
	s_branch .LBB0_1053

.LBB0_1076:
	s_or_b32 s6, s72, 1
	s_cmpk_lt_u32 s6, 0x201
	s_cselect_b64 s[30:31], -1, 0
	s_cmpk_gt_u32 s6, 0x200
	s_cbranch_scc1 .LBB0_1079
	s_lshl_b32 s6, s6, 4
	v_cmp_eq_u32_e32 vcc, s6, v80
	s_waitcnt vmcnt(8)
	v_lshlrev_b32_e32 v24, 16, v38
	v_and_b32_e32 v25, 0xffff0000, v38
	v_cndmask_b32_e64 v22, 1.0, 0, vcc
	v_lshlrev_b32_e32 v82, 16, v39
	v_and_b32_e32 v83, 0xffff0000, v39
	s_waitcnt vmcnt(5)
	v_lshlrev_b32_e32 v92, 16, v36
	v_and_b32_e32 v93, 0xffff0000, v36
	v_xor_b32_e32 v109, 0x80000000, v25
	v_xor_b32_e32 v108, 0x80000000, v24
	s_waitcnt vmcnt(12)
	v_lshlrev_b32_e32 v86, 16, v41
	v_and_b32_e32 v87, 0xffff0000, v41
	v_lshlrev_b32_e32 v94, 16, v37
	v_and_b32_e32 v95, 0xffff0000, v37
	v_pk_fma_f32 v[92:93], v[22:23], v[92:93], v[108:109] op_sel_hi:[0,1,1]
	v_xor_b32_e32 v109, 0x80000000, v83
	v_xor_b32_e32 v108, 0x80000000, v82
	v_lshlrev_b32_e32 v84, 16, v40
	v_and_b32_e32 v85, 0xffff0000, v40
	s_waitcnt vmcnt(4)
	v_lshlrev_b32_e32 v98, 16, v45
	v_and_b32_e32 v99, 0xffff0000, v45
	v_pk_fma_f32 v[94:95], v[22:23], v[94:95], v[108:109] op_sel_hi:[0,1,1]
	v_pk_fma_f32 v[92:93], v[2:3], v[92:93], v[24:25]
	v_xor_b32_e32 v25, 0x80000000, v87
	v_xor_b32_e32 v24, 0x80000000, v86
	s_waitcnt vmcnt(11)
	v_lshlrev_b32_e32 v88, 16, v42
	v_and_b32_e32 v89, 0xffff0000, v42
	v_lshlrev_b32_e32 v96, 16, v44
	v_and_b32_e32 v97, 0xffff0000, v44
	v_pk_fma_f32 v[94:95], v[4:5], v[94:95], v[82:83]
	v_pk_fma_f32 v[24:25], v[22:23], v[98:99], v[24:25] op_sel_hi:[0,1,1]
	v_xor_b32_e32 v83, 0x80000000, v85
	v_xor_b32_e32 v82, 0x80000000, v84
	v_lshlrev_b32_e32 v90, 16, v43
	v_and_b32_e32 v91, 0xffff0000, v43
	s_waitcnt vmcnt(3)
	v_lshlrev_b32_e32 v100, 16, v46
	v_and_b32_e32 v101, 0xffff0000, v46
	v_pk_fma_f32 v[82:83], v[22:23], v[96:97], v[82:83] op_sel_hi:[0,1,1]
	v_pk_fma_f32 v[98:99], v[8:9], v[24:25], v[86:87]
	v_xor_b32_e32 v25, 0x80000000, v89
	v_xor_b32_e32 v24, 0x80000000, v88
	v_lshlrev_b32_e32 v102, 16, v47
	v_and_b32_e32 v103, 0xffff0000, v47
	v_pk_fma_f32 v[96:97], v[6:7], v[82:83], v[84:85]
	v_pk_fma_f32 v[82:83], v[22:23], v[100:101], v[24:25] op_sel_hi:[0,1,1]
	v_xor_b32_e32 v25, 0x80000000, v91
	v_xor_b32_e32 v24, 0x80000000, v90
	s_waitcnt vmcnt(2)
	v_lshlrev_b32_e32 v28, 16, v48
	s_waitcnt vmcnt(1)
	v_lshlrev_b32_e32 v104, 16, v58
	v_and_b32_e32 v105, 0xffff0000, v58
	v_pk_fma_f32 v[22:23], v[22:23], v[102:103], v[24:25] op_sel_hi:[0,1,1]
	v_and_b32_e32 v81, 0xffff0000, v48
	v_pk_fma_f32 v[24:25], v[20:21], v[22:23], v[90:91]
	v_pk_fma_f32 v[22:23], v[18:19], v[82:83], v[88:89]
	v_pk_add_f32 v[82:83], v[104:105], -1.0 op_sel_hi:[1,0]
	v_mul_f32_e32 v28, 0xbfb8aa3b, v28
	v_lshlrev_b32_e32 v110, 16, v49
	v_pk_fma_f32 v[90:91], v[14:15], v[82:83], 1.0 op_sel_hi:[1,1,0]
	v_exp_f32_e32 v82, v28
	v_mul_f32_e32 v28, 0xbfb8aa3b, v81
	v_and_b32_e32 v111, 0xffff0000, v49
	v_exp_f32_e32 v83, v28
	v_mul_f32_e32 v28, 0xbfb8aa3b, v110
	v_exp_f32_e32 v84, v28
	v_mul_f32_e32 v28, 0xbfb8aa3b, v111
	v_exp_f32_e32 v85, v28
	v_lshlrev_b32_e32 v106, 16, v59
	v_and_b32_e32 v107, 0xffff0000, v59
	v_pk_add_f32 v[86:87], v[106:107], -1.0 op_sel_hi:[1,0]
	ds_write_b128 v73, v[82:85] offset:20480
	v_pk_mul_f32 v[82:83], v[12:13], v[98:99] neg_lo:[0,1] neg_hi:[0,1]
	v_pk_fma_f32 v[86:87], v[16:17], v[86:87], 1.0 op_sel_hi:[1,1,0]
	s_waitcnt vmcnt(0)
	v_pk_mul_f32 v[84:85], v[62:63], v[82:83] op_sel_hi:[0,1]
	v_pk_mul_f32 v[82:83], v[10:11], v[96:97] neg_lo:[0,1] neg_hi:[0,1]
	v_pk_mul_f32 v[88:89], v[98:99], v[86:87]
	v_pk_mul_f32 v[82:83], v[62:63], v[82:83] op_sel_hi:[0,1]
	ds_write_b128 v73, v[82:85] offset:20736
	v_pk_mul_f32 v[84:85], v[84:85], v[106:107] neg_lo:[1,0] neg_hi:[1,0]
	v_pk_mul_f32 v[82:83], v[82:83], v[104:105] neg_lo:[1,0] neg_hi:[1,0]
	v_pk_mul_f32 v[86:87], v[96:97], v[90:91]
	ds_write_b128 v73, v[82:85] offset:20992
	ds_write_b128 v73, v[86:89] offset:21248
	ds_write_b32 v114, v22 offset:4096
	ds_write_b32 v115, v23 offset:4096
	ds_write_b32 v116, v24 offset:4096
	ds_write_b32 v117, v25 offset:4096
	v_cvt_pk_bf16_f32 v22, v92, v93
	v_cvt_pk_bf16_f32 v23, v94, v95
	s_cmpk_gt_u32 s72, 0x1fd
	ds_write_b64 v75, v[22:23] offset:43008
	s_cbranch_scc1 .LBB0_1079
	v_lshl_add_u32 v28, s72, 4, v77
	v_add_u32_e32 v24, -1, v28
	v_mad_u64_u32 v[22:23], s[6:7], v28, s63, v[30:31]
	v_mad_u64_u32 v[24:25], s[6:7], v24, s63, v[30:31]
	global_load_dwordx2 v[38:39], v[22:23], off
	global_load_dwordx2 v[40:41], v[22:23], off offset:1024
	global_load_dwordx2 v[42:43], v[22:23], off offset:2048
	global_load_dwordx2 v[36:37], v[24:25], off
	v_lshlrev_b64 v[22:23], 10, v[28:29]
	v_lshl_add_u64 v[48:49], v[32:33], 0, v[22:23]
	v_lshl_add_u64 v[22:23], v[34:35], 0, v[22:23]
	global_load_dwordx2 v[44:45], v[24:25], off offset:1024
	global_load_dwordx2 v[46:47], v[24:25], off offset:2048
	s_nop 0
	global_load_dwordx2 v[48:49], v[48:49], off
	s_nop 0
	global_load_dwordx2 v[58:59], v[22:23], off
	v_lshlrev_b64 v[22:23], 5, v[28:29]
	v_lshl_add_u64 v[22:23], s[36:37], 0, v[22:23]
	global_load_dword v62, v[22:23], off

.LBB0_1091:
	s_waitcnt vmcnt(8)
	v_lshlrev_b32_e32 v24, 16, v51
	v_and_b32_e32 v25, 0xffff0000, v51
	s_waitcnt vmcnt(5)
	v_lshlrev_b32_e32 v96, 16, v57
	v_and_b32_e32 v97, 0xffff0000, v57
	v_lshlrev_b32_e32 v22, 16, v50
	v_and_b32_e32 v23, 0xffff0000, v50
	v_lshlrev_b32_e32 v82, 16, v52
	v_and_b32_e32 v83, 0xffff0000, v52
	v_lshlrev_b32_e32 v28, 16, v56
	v_and_b32_e32 v81, 0xffff0000, v56
	s_waitcnt vmcnt(4)
	v_lshlrev_b32_e32 v98, 16, v60
	v_and_b32_e32 v99, 0xffff0000, v60
	v_sub_f32_e32 v97, v97, v25
	v_sub_f32_e32 v96, v96, v24
	v_lshlrev_b32_e32 v84, 16, v53
	v_and_b32_e32 v85, 0xffff0000, v53
	v_lshlrev_b32_e32 v100, 16, v61
	v_and_b32_e32 v101, 0xffff0000, v61
	s_waitcnt vmcnt(2)
	v_lshlrev_b32_e32 v106, 16, v66
	s_waitcnt vmcnt(1)
	v_lshlrev_b32_e32 v90, 16, v68
	v_and_b32_e32 v91, 0xffff0000, v68
	v_sub_f32_e32 v95, v81, v23
	v_sub_f32_e32 v94, v28, v22
	v_pk_fma_f32 v[96:97], v[4:5], v[96:97], v[24:25]
	v_sub_f32_e32 v25, v99, v83
	v_sub_f32_e32 v24, v98, v82
	v_lshlrev_b32_e32 v86, 16, v54
	v_and_b32_e32 v87, 0xffff0000, v54
	v_lshlrev_b32_e32 v102, 16, v64
	v_and_b32_e32 v103, 0xffff0000, v64
	v_and_b32_e32 v107, 0xffff0000, v66
	v_pk_fma_f32 v[94:95], v[2:3], v[94:95], v[22:23]
	v_sub_f32_e32 v23, v101, v85
	v_sub_f32_e32 v22, v100, v84
	v_pk_fma_f32 v[98:99], v[6:7], v[24:25], v[82:83]
	v_pk_add_f32 v[82:83], v[90:91], -1.0 op_sel_hi:[1,0]
	v_mul_f32_e32 v28, 0xbfb8aa3b, v106
	v_lshlrev_b32_e32 v108, 16, v67
	v_pk_fma_f32 v[100:101], v[8:9], v[22:23], v[84:85]
	v_sub_f32_e32 v23, v103, v87
	v_sub_f32_e32 v22, v102, v86
	v_pk_fma_f32 v[102:103], v[14:15], v[82:83], 1.0 op_sel_hi:[1,1,0]
	v_exp_f32_e32 v82, v28
	v_mul_f32_e32 v28, 0xbfb8aa3b, v107
	v_and_b32_e32 v109, 0xffff0000, v67
	v_exp_f32_e32 v83, v28
	v_mul_f32_e32 v28, 0xbfb8aa3b, v108
	v_exp_f32_e32 v84, v28
	v_mul_f32_e32 v28, 0xbfb8aa3b, v109
	v_exp_f32_e32 v85, v28
	v_lshlrev_b32_e32 v92, 16, v69
	v_and_b32_e32 v93, 0xffff0000, v69
	v_lshlrev_b32_e32 v88, 16, v55
	ds_write_b128 v73, v[82:85]
	v_pk_mul_f32 v[82:83], v[12:13], v[100:101] neg_lo:[0,1] neg_hi:[0,1]
	v_and_b32_e32 v89, 0xffff0000, v55
	s_waitcnt vmcnt(0)
	v_pk_mul_f32 v[84:85], v[70:71], v[82:83] op_sel_hi:[0,1]
	v_pk_mul_f32 v[82:83], v[10:11], v[98:99] neg_lo:[0,1] neg_hi:[0,1]
	v_lshlrev_b32_e32 v104, 16, v65
	v_and_b32_e32 v105, 0xffff0000, v65
	v_pk_fma_f32 v[22:23], v[18:19], v[22:23], v[86:87]
	v_pk_add_f32 v[86:87], v[92:93], -1.0 op_sel_hi:[1,0]
	v_pk_mul_f32 v[82:83], v[70:71], v[82:83] op_sel_hi:[0,1]
	v_sub_f32_e32 v25, v105, v89
	v_sub_f32_e32 v24, v104, v88
	v_pk_fma_f32 v[86:87], v[16:17], v[86:87], 1.0 op_sel_hi:[1,1,0]
	ds_write_b128 v73, v[82:85] offset:256
	v_pk_mul_f32 v[84:85], v[84:85], v[92:93] neg_lo:[1,0] neg_hi:[1,0]
	v_pk_mul_f32 v[82:83], v[82:83], v[90:91] neg_lo:[1,0] neg_hi:[1,0]
	v_pk_fma_f32 v[24:25], v[20:21], v[24:25], v[88:89]
	v_pk_mul_f32 v[88:89], v[100:101], v[86:87]
	v_pk_mul_f32 v[86:87], v[98:99], v[102:103]
	ds_write_b128 v73, v[82:85] offset:512
	ds_write_b128 v73, v[86:89] offset:768
	ds_write_b32 v114, v22
	ds_write_b32 v115, v23
	ds_write_b32 v116, v24
	ds_write_b32 v117, v25
	v_cvt_pk_bf16_f32 v22, v94, v95
	v_cvt_pk_bf16_f32 v23, v96, v97
	s_cmpk_gt_u32 s72, 0x1fc
	ds_write_b64 v75, v[22:23] offset:40960
	s_cbranch_scc1 .LBB0_1051
	v_add_u32_e32 v22, s10, v78
	v_add_u32_e32 v28, -1, v22
	v_ashrrev_i32_e32 v23, 31, v22
	v_mad_i64_i32 v[24:25], s[6:7], v22, s63, v[30:31]
	v_mad_u64_u32 v[64:65], s[6:7], v28, s63, v[30:31]
	global_load_dwordx2 v[50:51], v[24:25], off
	global_load_dwordx2 v[52:53], v[24:25], off offset:1024
	global_load_dwordx2 v[54:55], v[24:25], off offset:2048
	global_load_dwordx2 v[56:57], v[64:65], off
	v_lshlrev_b64 v[24:25], 10, v[22:23]
	v_lshl_add_u64 v[66:67], v[32:33], 0, v[24:25]
	v_lshl_add_u64 v[24:25], v[34:35], 0, v[24:25]
	global_load_dwordx2 v[60:61], v[64:65], off offset:1024
	s_nop 0
	global_load_dwordx2 v[64:65], v[64:65], off offset:2048
	s_nop 0
	global_load_dwordx2 v[66:67], v[66:67], off
	s_nop 0
	global_load_dwordx2 v[68:69], v[24:25], off
	v_lshlrev_b64 v[22:23], 5, v[22:23]
	v_lshl_add_u64 v[22:23], s[36:37], 0, v[22:23]
	global_load_dword v70, v[22:23], off
	s_branch .LBB0_1051

.LBB0_1103:
	s_add_u32 s40, s28, 0x6a00000
	s_addc_u32 s41, s29, 0
	s_add_u32 s46, s28, 0x7f00000
	s_addc_u32 s47, s29, 0
	s_add_u32 s36, s28, 0x8a00000
	s_addc_u32 s37, s29, 0
	v_readlane_b32 s0, v255, 3
	s_add_u32 s56, s28, 0xfd20000
	v_readlane_b32 s1, v255, 4
	s_addc_u32 s57, s29, 0
	s_andn2_b64 vcc, exec, s[0:1]
	s_cbranch_vccnz .LBB0_1531
	v_readlane_b32 s0, v255, 25
	v_mov_b32_e32 v3, 0
	v_readlane_b32 s1, v255, 26
	v_readlane_b32 s31, v255, 0
	s_bfe_u32 s10, s31, 0x20006
	v_lshl_add_u32 v149, v178, 2, 0
	v_or_b32_e32 v5, 0x200, v0
	s_lshl_b32 s64, s10, 5
	global_load_dword v174, v3, s[0:1]
	s_lshr_b32 s0, s31, 8
	s_lshl_b32 s65, s0, 7
	v_readlane_b32 s52, v255, 38
	v_lshlrev_b32_e32 v2, 4, v169
	v_lshlrev_b32_e32 v6, 4, v133
	s_movk_i32 s11, 0x110
	s_movk_i32 s30, 0x88
	v_lshrrev_b32_e32 v213, 4, v5
	v_lshl_add_u32 v216, s10, 14, v149
	v_readlane_b32 s53, v255, 39
	s_add_u32 s10, s52, s65
	v_lshrrev_b32_e32 v4, 5, v178
	v_mad_u32_u24 v212, v172, s11, v2
	v_mad_u32_u24 v215, v168, s30, v6
	v_lshl_add_u64 v[180:181], s[84:85], 0, v[2:3]
	v_mad_u32_u24 v217, v213, s11, v2
	v_lshlrev_b32_e32 v2, 1, v132
	s_addc_u32 s11, s53, 0
	v_lshlrev_b32_e32 v163, 3, v4
	v_lshlrev_b32_e32 v176, 4, v4
	v_lshlrev_b32_e32 v178, 2, v4
	v_lshrrev_b32_e32 v214, 3, v5
	v_add_u32_e32 v4, 0, v215
	v_lshl_add_u64 v[184:185], s[8:9], 0, v[2:3]
	v_lshlrev_b32_e32 v2, 4, v167
	s_cmp_eq_u32 s0, 1
	v_mov_b32_e32 v177, v3
	v_mov_b32_e32 v5, v3
	v_mad_u32_u24 v218, v214, s30, v6
	v_readlane_b32 s68, v255, 7
	v_add_u32_e32 v167, 0x4400, v4
	v_lshl_or_b32 v4, v172, 8, v2
	s_cselect_b64 s[8:9], -1, 0
	s_cmpk_lt_u32 s31, 0x100
	v_and_b32_e32 v147, 31, v0
	s_mov_b64 s[6:7], 0x9fa4000
	v_readlane_b32 s80, v255, 19
	v_readlane_b32 s81, v255, 20
	v_add_u32_e32 v8, 0, v218
	v_lshl_add_u64 v[186:187], s[10:11], 0, v[176:177]
	v_lshl_add_u64 v[6:7], s[28:29], 0, v[2:3]
	v_lshl_add_u64 v[4:5], s[28:29], 0, v[4:5]
	s_cselect_b64 s[58:59], -1, 0
	s_and_b32 s0, s31, 0xc0
	s_lshl_b32 s10, s31, 8
	s_add_i32 s66, 0, 0x23000
	v_readlane_b32 s52, v255, 23
	s_mov_b32 s1, 0
	s_movk_i32 s35, 0x1ff
	s_movk_i32 s62, 0x4080
	s_mov_b64 s[4:5], 0x4000
	v_mov_b32_e32 v151, 0x358637bd
	s_mov_b32 s63, 0x800000
	v_mov_b32_e32 v153, 0x150
	v_mov_b32_e32 v159, 0x204000
	v_mov_b32_e32 v161, 0xf149f2ca
	v_mul_u32_u24_e32 v165, 0x110, v147
	v_mul_u32_u24_e32 v171, 0x88, v147
	v_lshl_add_u64 v[182:183], s[80:81], 0, v[176:177]
	v_or_b32_e32 v219, s64, v147
	v_add_u32_e32 v220, 0, v212
	v_add_u32_e32 v221, 0, v217
	v_add_u32_e32 v177, 0x4400, v8
	v_lshl_add_u64 v[188:189], v[6:7], 0, s[6:7]
	v_lshl_add_u64 v[190:191], v[4:5], 0, s[6:7]
	v_lshl_add_u32 v222, s0, 8, v149
	s_or_b32 s67, s10, 0x3f00
	v_mov_b32_e32 v223, s66
	v_mbcnt_hi_u32_b32 v157, -1, v211
	v_readlane_b32 s53, v255, 24
	v_readlane_b32 s69, v255, 8
	v_readlane_b32 s70, v255, 9
	v_readlane_b32 s71, v255, 10
	v_readlane_b32 s72, v255, 11
	v_readlane_b32 s73, v255, 12
	v_readlane_b32 s74, v255, 13
	v_readlane_b32 s75, v255, 14
	v_readlane_b32 s76, v255, 15
	v_readlane_b32 s77, v255, 16
	s_waitcnt vmcnt(0)
	v_mov_b32_e32 v175, v174
	v_readlane_b32 s78, v255, 17
	v_readlane_b32 s79, v255, 18
	v_readlane_b32 s82, v255, 21
	v_readlane_b32 s83, v255, 22
	s_branch .LBB0_1107
	s_nop 0
	s_nop 0
	s_nop 0
	s_nop 0
	s_nop 0
	s_nop 0
	s_nop 0
